# GEMM main loops: MFMAs of one accumulator issued back to back (pure reorder); plus earlier edits
# speedup vs baseline: 1.0061x; 1.0061x over previous
.LBB0_446:
	s_add_u32 s20, s56, 0xfff50080
	s_addc_u32 s21, s57, -1
	s_add_i32 s22, 0, 0x10000
	s_cmp_eq_u32 s84, 40
	s_cselect_b32 s61, s49, s21
	s_cselect_b32 s60, s48, s20
	s_cselect_b32 s21, s51, s63
	s_cselect_b32 s20, s50, s62
	s_add_i32 s23, 0, 0x14000
	v_add_u32_e32 v134, s22, v191
	v_add_u32_e32 v162, s23, v191
	ds_read_b128 v[114:117], v134
	ds_read_b128 v[126:129], v134 offset:1024
	ds_read_b128 v[130:133], v134 offset:2048
	ds_read_b128 v[134:137], v134 offset:3072
	ds_read_b128 v[146:149], v162
	ds_read_b128 v[150:153], v162 offset:1024
	ds_read_b128 v[158:161], v162 offset:2048
	ds_read_b128 v[182:185], v162 offset:3072
	v_lshl_add_u64 v[162:163], s[56:57], 0, v[156:157]
	s_add_i32 m0, s47, 0xc000
	ds_read_b128 v[186:189], v193
	ds_read_b128 v[194:197], v193 offset:1024
	ds_read_b128 v[198:201], v193 offset:2048
	ds_read_b128 v[214:217], v193 offset:3072
	ds_read_b128 v[218:221], v193 offset:4096
	ds_read_b128 v[222:225], v193 offset:5120
	ds_read_b128 v[226:229], v193 offset:6144
	ds_read_b128 v[230:233], v193 offset:7168
	global_load_lds_dwordx4 v[162:163], off
	v_lshl_add_u64 v[162:163], v[162:163], 0, s[2:3]
	s_add_i32 m0, s47, 0xe000
	s_nop 0
	global_load_lds_dwordx4 v[162:163], off
	s_waitcnt vmcnt(8)
	s_waitcnt lgkmcnt(0)
	s_barrier
	s_setprio 1
	s_waitcnt lgkmcnt(0)
	v_mfma_f32_16x16x32_bf16 v[142:145], v[114:117], v[186:189], v[142:145]
	v_mfma_f32_16x16x32_bf16 v[142:145], v[126:129], v[194:197], v[142:145]
	v_mfma_f32_16x16x32_bf16 v[138:141], v[130:133], v[186:189], v[138:141]
	v_mfma_f32_16x16x32_bf16 v[138:141], v[134:137], v[194:197], v[138:141]
	v_mfma_f32_16x16x32_bf16 v[110:113], v[114:117], v[198:201], v[110:113]
	v_mfma_f32_16x16x32_bf16 v[110:113], v[126:129], v[214:217], v[110:113]
	v_mfma_f32_16x16x32_bf16 v[106:109], v[130:133], v[198:201], v[106:109]
	v_mfma_f32_16x16x32_bf16 v[106:109], v[134:137], v[214:217], v[106:109]
	v_mfma_f32_16x16x32_bf16 v[94:97], v[114:117], v[218:221], v[94:97]
	v_mfma_f32_16x16x32_bf16 v[94:97], v[126:129], v[222:225], v[94:97]
	v_mfma_f32_16x16x32_bf16 v[90:93], v[130:133], v[218:221], v[90:93]
	v_mfma_f32_16x16x32_bf16 v[90:93], v[134:137], v[222:225], v[90:93]
	v_mfma_f32_16x16x32_bf16 v[78:81], v[114:117], v[226:229], v[78:81]
	v_mfma_f32_16x16x32_bf16 v[78:81], v[126:129], v[230:233], v[78:81]
	v_mfma_f32_16x16x32_bf16 v[74:77], v[130:133], v[226:229], v[74:77]
	v_mfma_f32_16x16x32_bf16 v[74:77], v[134:137], v[230:233], v[74:77]
	s_setprio 0
	s_setprio 1
	v_mfma_f32_16x16x32_bf16 v[122:125], v[146:149], v[186:189], v[122:125]
	v_mfma_f32_16x16x32_bf16 v[122:125], v[150:153], v[194:197], v[122:125]
	v_mfma_f32_16x16x32_bf16 v[118:121], v[158:161], v[186:189], v[118:121]
	v_mfma_f32_16x16x32_bf16 v[118:121], v[182:185], v[194:197], v[118:121]
	v_mfma_f32_16x16x32_bf16 v[102:105], v[146:149], v[198:201], v[102:105]
	v_mfma_f32_16x16x32_bf16 v[102:105], v[150:153], v[214:217], v[102:105]
	v_mfma_f32_16x16x32_bf16 v[98:101], v[158:161], v[198:201], v[98:101]
	v_mfma_f32_16x16x32_bf16 v[98:101], v[182:185], v[214:217], v[98:101]
	v_mfma_f32_16x16x32_bf16 v[86:89], v[146:149], v[218:221], v[86:89]
	v_mfma_f32_16x16x32_bf16 v[86:89], v[150:153], v[222:225], v[86:89]
	v_mfma_f32_16x16x32_bf16 v[82:85], v[158:161], v[218:221], v[82:85]
	v_mfma_f32_16x16x32_bf16 v[82:85], v[182:185], v[222:225], v[82:85]
	v_mfma_f32_16x16x32_bf16 v[70:73], v[146:149], v[226:229], v[70:73]
	v_mfma_f32_16x16x32_bf16 v[70:73], v[150:153], v[230:233], v[70:73]
	v_mfma_f32_16x16x32_bf16 v[66:69], v[158:161], v[226:229], v[66:69]
	v_mfma_f32_16x16x32_bf16 v[66:69], v[182:185], v[230:233], v[66:69]
	s_setprio 0
	s_barrier
	v_lshl_add_u64 v[162:163], s[20:21], 0, v[0:1]
	s_add_i32 s20, s22, s46
	s_mov_b32 m0, s20
	ds_read_b128 v[186:189], v193 offset:16384
	ds_read_b128 v[194:197], v193 offset:17408
	ds_read_b128 v[198:201], v193 offset:18432
	ds_read_b128 v[214:217], v193 offset:19456
	ds_read_b128 v[218:221], v193 offset:20480
	ds_read_b128 v[222:225], v193 offset:21504
	ds_read_b128 v[226:229], v193 offset:22528
	ds_read_b128 v[230:233], v193 offset:23552
	global_load_lds_dwordx4 v[162:163], off
	v_lshl_add_u64 v[202:203], v[162:163], 0, s[2:3]
	s_add_i32 m0, s20, 0x2000
	s_add_i32 s20, s23, s46
	global_load_lds_dwordx4 v[202:203], off
	v_lshl_add_u64 v[202:203], v[162:163], 0, s[12:13]
	s_mov_b32 m0, s20
	s_nop 0
	global_load_lds_dwordx4 v[202:203], off
	v_lshl_add_u64 v[202:203], v[162:163], 0, s[86:87]
	s_add_i32 m0, s20, 0x2000
	s_nop 0
	global_load_lds_dwordx4 v[202:203], off
	v_lshl_add_u64 v[202:203], s[60:61], 0, v[154:155]
	s_mov_b32 m0, s47
	v_lshl_add_u64 v[234:235], v[202:203], 0, s[2:3]
	global_load_lds_dwordx4 v[202:203], off
	s_mov_b32 m0, s68
	s_nop 0
	global_load_lds_dwordx4 v[234:235], off
	s_waitcnt vmcnt(8)
	s_waitcnt lgkmcnt(0)
	s_barrier
	s_setprio 1
	s_waitcnt lgkmcnt(0)
	v_mfma_f32_16x16x32_bf16 v[62:65], v[114:117], v[186:189], v[62:65]
	v_mfma_f32_16x16x32_bf16 v[62:65], v[126:129], v[194:197], v[62:65]
	v_mfma_f32_16x16x32_bf16 v[58:61], v[130:133], v[186:189], v[58:61]
	v_mfma_f32_16x16x32_bf16 v[58:61], v[134:137], v[194:197], v[58:61]
	v_mfma_f32_16x16x32_bf16 v[46:49], v[114:117], v[198:201], v[46:49]
	v_mfma_f32_16x16x32_bf16 v[46:49], v[126:129], v[214:217], v[46:49]
	v_mfma_f32_16x16x32_bf16 v[42:45], v[130:133], v[198:201], v[42:45]
	v_mfma_f32_16x16x32_bf16 v[42:45], v[134:137], v[214:217], v[42:45]
	v_mfma_f32_16x16x32_bf16 v[30:33], v[114:117], v[218:221], v[30:33]
	v_mfma_f32_16x16x32_bf16 v[30:33], v[126:129], v[222:225], v[30:33]
	v_mfma_f32_16x16x32_bf16 v[26:29], v[130:133], v[218:221], v[26:29]
	v_mfma_f32_16x16x32_bf16 v[26:29], v[134:137], v[222:225], v[26:29]
	v_mfma_f32_16x16x32_bf16 v[14:17], v[114:117], v[226:229], v[14:17]
	v_mfma_f32_16x16x32_bf16 v[14:17], v[126:129], v[230:233], v[14:17]
	v_mfma_f32_16x16x32_bf16 v[10:13], v[130:133], v[226:229], v[10:13]
	v_mfma_f32_16x16x32_bf16 v[10:13], v[134:137], v[230:233], v[10:13]
	s_setprio 0
	s_setprio 1
	v_mfma_f32_16x16x32_bf16 v[54:57], v[146:149], v[186:189], v[54:57]
	v_mfma_f32_16x16x32_bf16 v[54:57], v[150:153], v[194:197], v[54:57]
	v_mfma_f32_16x16x32_bf16 v[50:53], v[158:161], v[186:189], v[50:53]
	v_mfma_f32_16x16x32_bf16 v[50:53], v[182:185], v[194:197], v[50:53]
	v_mfma_f32_16x16x32_bf16 v[38:41], v[146:149], v[198:201], v[38:41]
	v_mfma_f32_16x16x32_bf16 v[38:41], v[150:153], v[214:217], v[38:41]
	v_mfma_f32_16x16x32_bf16 v[34:37], v[158:161], v[198:201], v[34:37]
	v_mfma_f32_16x16x32_bf16 v[34:37], v[182:185], v[214:217], v[34:37]
	v_mfma_f32_16x16x32_bf16 v[22:25], v[146:149], v[218:221], v[22:25]
	v_mfma_f32_16x16x32_bf16 v[22:25], v[150:153], v[222:225], v[22:25]
	v_mfma_f32_16x16x32_bf16 v[18:21], v[158:161], v[218:221], v[18:21]
	v_mfma_f32_16x16x32_bf16 v[18:21], v[182:185], v[222:225], v[18:21]
	v_mfma_f32_16x16x32_bf16 v[6:9], v[146:149], v[226:229], v[6:9]
	v_mfma_f32_16x16x32_bf16 v[6:9], v[150:153], v[230:233], v[6:9]
	v_mfma_f32_16x16x32_bf16 v[2:5], v[158:161], v[226:229], v[2:5]
	v_mfma_f32_16x16x32_bf16 v[2:5], v[182:185], v[230:233], v[2:5]
	s_setprio 0
	s_barrier
	s_add_i32 s20, 0, 0x18000
	s_add_i32 s21, 0, 0x1c000
	v_add_u32_e32 v134, s20, v191
	v_add_u32_e32 v182, s21, v191
	ds_read_b128 v[114:117], v134
	ds_read_b128 v[126:129], v134 offset:1024
	ds_read_b128 v[130:133], v134 offset:2048
	ds_read_b128 v[134:137], v134 offset:3072
	ds_read_b128 v[146:149], v182
	ds_read_b128 v[150:153], v182 offset:1024
	ds_read_b128 v[158:161], v182 offset:2048
	ds_read_b128 v[182:185], v182 offset:3072
	s_mov_b32 m0, s69
	v_lshl_add_u64 v[234:235], v[202:203], 0, s[12:13]
	ds_read_b128 v[186:189], v193 offset:32768
	ds_read_b128 v[194:197], v193 offset:33792
	ds_read_b128 v[198:201], v193 offset:34816
	ds_read_b128 v[214:217], v193 offset:35840
	ds_read_b128 v[218:221], v193 offset:36864
	ds_read_b128 v[222:225], v193 offset:37888
	ds_read_b128 v[226:229], v193 offset:38912
	ds_read_b128 v[230:233], v193 offset:39936
	global_load_lds_dwordx4 v[234:235], off
	v_lshl_add_u64 v[234:235], v[202:203], 0, s[86:87]
	s_mov_b32 m0, s76
	s_nop 0
	global_load_lds_dwordx4 v[234:235], off
	s_waitcnt vmcnt(8)
	s_waitcnt lgkmcnt(0)
	s_barrier
	s_setprio 1
	s_waitcnt lgkmcnt(0)
	v_mfma_f32_16x16x32_bf16 v[142:145], v[114:117], v[186:189], v[142:145]
	v_mfma_f32_16x16x32_bf16 v[142:145], v[126:129], v[194:197], v[142:145]
	v_mfma_f32_16x16x32_bf16 v[138:141], v[130:133], v[186:189], v[138:141]
	v_mfma_f32_16x16x32_bf16 v[138:141], v[134:137], v[194:197], v[138:141]
	v_mfma_f32_16x16x32_bf16 v[110:113], v[114:117], v[198:201], v[110:113]
	v_mfma_f32_16x16x32_bf16 v[110:113], v[126:129], v[214:217], v[110:113]
	v_mfma_f32_16x16x32_bf16 v[106:109], v[130:133], v[198:201], v[106:109]
	v_mfma_f32_16x16x32_bf16 v[106:109], v[134:137], v[214:217], v[106:109]
	v_mfma_f32_16x16x32_bf16 v[94:97], v[114:117], v[218:221], v[94:97]
	v_mfma_f32_16x16x32_bf16 v[94:97], v[126:129], v[222:225], v[94:97]
	v_mfma_f32_16x16x32_bf16 v[90:93], v[130:133], v[218:221], v[90:93]
	v_mfma_f32_16x16x32_bf16 v[90:93], v[134:137], v[222:225], v[90:93]
	v_mfma_f32_16x16x32_bf16 v[78:81], v[114:117], v[226:229], v[78:81]
	v_mfma_f32_16x16x32_bf16 v[78:81], v[126:129], v[230:233], v[78:81]
	v_mfma_f32_16x16x32_bf16 v[74:77], v[130:133], v[226:229], v[74:77]
	v_mfma_f32_16x16x32_bf16 v[74:77], v[134:137], v[230:233], v[74:77]
	s_setprio 0
	s_setprio 1
	v_mfma_f32_16x16x32_bf16 v[122:125], v[146:149], v[186:189], v[122:125]
	v_mfma_f32_16x16x32_bf16 v[122:125], v[150:153], v[194:197], v[122:125]
	v_mfma_f32_16x16x32_bf16 v[118:121], v[158:161], v[186:189], v[118:121]
	v_mfma_f32_16x16x32_bf16 v[118:121], v[182:185], v[194:197], v[118:121]
	v_mfma_f32_16x16x32_bf16 v[102:105], v[146:149], v[198:201], v[102:105]
	v_mfma_f32_16x16x32_bf16 v[102:105], v[150:153], v[214:217], v[102:105]
	v_mfma_f32_16x16x32_bf16 v[98:101], v[158:161], v[198:201], v[98:101]
	v_mfma_f32_16x16x32_bf16 v[98:101], v[182:185], v[214:217], v[98:101]
	v_mfma_f32_16x16x32_bf16 v[86:89], v[146:149], v[218:221], v[86:89]
	v_mfma_f32_16x16x32_bf16 v[86:89], v[150:153], v[222:225], v[86:89]
	v_mfma_f32_16x16x32_bf16 v[82:85], v[158:161], v[218:221], v[82:85]
	v_mfma_f32_16x16x32_bf16 v[82:85], v[182:185], v[222:225], v[82:85]
	v_mfma_f32_16x16x32_bf16 v[70:73], v[146:149], v[226:229], v[70:73]
	v_mfma_f32_16x16x32_bf16 v[70:73], v[150:153], v[230:233], v[70:73]
	v_mfma_f32_16x16x32_bf16 v[66:69], v[158:161], v[226:229], v[66:69]
	v_mfma_f32_16x16x32_bf16 v[66:69], v[182:185], v[230:233], v[66:69]
	s_setprio 0
	s_barrier
	s_add_i32 s20, s20, s46
	v_lshl_add_u64 v[234:235], v[162:163], 0, s[34:35]
	s_mov_b32 m0, s20
	ds_read_b128 v[186:189], v193 offset:49152
	ds_read_b128 v[194:197], v193 offset:50176
	ds_read_b128 v[198:201], v193 offset:51200
	ds_read_b128 v[214:217], v193 offset:52224
	ds_read_b128 v[218:221], v193 offset:53248
	ds_read_b128 v[222:225], v193 offset:54272
	ds_read_b128 v[226:229], v193 offset:55296
	ds_read_b128 v[230:233], v193 offset:56320
	global_load_lds_dwordx4 v[234:235], off
	v_lshl_add_u64 v[234:235], v[162:163], 0, s[96:97]
	s_add_i32 m0, s20, 0x2000
	s_add_i32 s20, s21, s46
	global_load_lds_dwordx4 v[234:235], off
	v_lshl_add_u64 v[234:235], v[162:163], 0, vcc
	s_mov_b32 m0, s20
	v_lshl_add_u64 v[162:163], v[162:163], 0, s[0:1]
	global_load_lds_dwordx4 v[234:235], off
	s_add_i32 m0, s20, 0x2000
	s_nop 0
	global_load_lds_dwordx4 v[162:163], off
	v_lshl_add_u64 v[162:163], v[202:203], 0, s[34:35]
	s_mov_b32 m0, s77
	s_nop 0
	global_load_lds_dwordx4 v[162:163], off
	v_lshl_add_u64 v[162:163], v[202:203], 0, s[96:97]
	s_mov_b32 m0, s78
	s_nop 0
	global_load_lds_dwordx4 v[162:163], off
	s_waitcnt vmcnt(8)
	s_waitcnt lgkmcnt(0)
	s_barrier
	s_setprio 1
	s_waitcnt lgkmcnt(0)
	v_mfma_f32_16x16x32_bf16 v[62:65], v[114:117], v[186:189], v[62:65]
	v_mfma_f32_16x16x32_bf16 v[62:65], v[126:129], v[194:197], v[62:65]
	v_mfma_f32_16x16x32_bf16 v[58:61], v[130:133], v[186:189], v[58:61]
	v_mfma_f32_16x16x32_bf16 v[58:61], v[134:137], v[194:197], v[58:61]
	v_mfma_f32_16x16x32_bf16 v[46:49], v[114:117], v[198:201], v[46:49]
	v_mfma_f32_16x16x32_bf16 v[46:49], v[126:129], v[214:217], v[46:49]
	v_mfma_f32_16x16x32_bf16 v[42:45], v[130:133], v[198:201], v[42:45]
	v_mfma_f32_16x16x32_bf16 v[42:45], v[134:137], v[214:217], v[42:45]
	v_mfma_f32_16x16x32_bf16 v[30:33], v[114:117], v[218:221], v[30:33]
	v_mfma_f32_16x16x32_bf16 v[30:33], v[126:129], v[222:225], v[30:33]
	v_mfma_f32_16x16x32_bf16 v[26:29], v[130:133], v[218:221], v[26:29]
	v_mfma_f32_16x16x32_bf16 v[26:29], v[134:137], v[222:225], v[26:29]
	v_mfma_f32_16x16x32_bf16 v[14:17], v[114:117], v[226:229], v[14:17]
	v_mfma_f32_16x16x32_bf16 v[14:17], v[126:129], v[230:233], v[14:17]
	v_mfma_f32_16x16x32_bf16 v[10:13], v[130:133], v[226:229], v[10:13]
	v_mfma_f32_16x16x32_bf16 v[10:13], v[134:137], v[230:233], v[10:13]
	s_setprio 0
	s_setprio 1
	v_mfma_f32_16x16x32_bf16 v[54:57], v[146:149], v[186:189], v[54:57]
	v_mfma_f32_16x16x32_bf16 v[54:57], v[150:153], v[194:197], v[54:57]
	v_mfma_f32_16x16x32_bf16 v[50:53], v[158:161], v[186:189], v[50:53]
	v_mfma_f32_16x16x32_bf16 v[50:53], v[182:185], v[194:197], v[50:53]
	v_mfma_f32_16x16x32_bf16 v[38:41], v[146:149], v[198:201], v[38:41]
	v_mfma_f32_16x16x32_bf16 v[38:41], v[150:153], v[214:217], v[38:41]
	v_mfma_f32_16x16x32_bf16 v[34:37], v[158:161], v[198:201], v[34:37]
	v_mfma_f32_16x16x32_bf16 v[34:37], v[182:185], v[214:217], v[34:37]
	v_mfma_f32_16x16x32_bf16 v[22:25], v[146:149], v[218:221], v[22:25]
	v_mfma_f32_16x16x32_bf16 v[22:25], v[150:153], v[222:225], v[22:25]
	v_mfma_f32_16x16x32_bf16 v[18:21], v[158:161], v[218:221], v[18:21]
	v_mfma_f32_16x16x32_bf16 v[18:21], v[182:185], v[222:225], v[18:21]
	v_mfma_f32_16x16x32_bf16 v[6:9], v[146:149], v[226:229], v[6:9]
	v_mfma_f32_16x16x32_bf16 v[6:9], v[150:153], v[230:233], v[6:9]
	v_mfma_f32_16x16x32_bf16 v[2:5], v[158:161], v[226:229], v[2:5]
	v_mfma_f32_16x16x32_bf16 v[2:5], v[182:185], v[230:233], v[2:5]
	s_setprio 0
	s_barrier
	s_add_i32 s84, s84, 2
	s_add_u32 s56, s56, 0x100
	s_addc_u32 s57, s57, 0
	s_add_u32 s62, s62, 0x100
	s_addc_u32 s63, s63, 0
	s_cmp_gt_u32 s84, 41
	s_cbranch_scc0 .LBB0_446
	s_and_b64 vcc, exec, s[40:41]
	s_cbranch_vccz .LBB0_449
	s_barrier

.LBB0_488:
	s_add_u32 s20, s68, 0xfffc0080
	s_addc_u32 s21, s69, -1
	s_add_i32 s22, 0, 0x10000
	s_cmp_eq_u32 s97, 12
	s_cselect_b32 s77, s57, s21
	s_cselect_b32 s76, s86, s20
	v_add_u32_e32 v143, s22, v139
	s_cselect_b32 s21, s51, s96
	s_cselect_b32 s20, s87, s91
	s_add_i32 s23, 0, 0x14000
	ds_read_b128 v[134:137], v143
	ds_read_b128 v[144:147], v143 offset:1024
	ds_read_b128 v[148:151], v143 offset:2048
	ds_read_b128 v[152:155], v143 offset:3072
	v_add_u32_e32 v143, s23, v139
	ds_read_b128 v[156:159], v143
	ds_read_b128 v[160:163], v143 offset:1024
	ds_read_b128 v[182:185], v143 offset:2048
	ds_read_b128 v[186:189], v143 offset:3072
	v_lshl_add_u64 v[202:203], s[68:69], 0, v[132:133]
	s_add_i32 m0, s43, 0xc000
	ds_read_b128 v[190:193], v142
	ds_read_b128 v[194:197], v142 offset:1024
	ds_read_b128 v[198:201], v142 offset:2048
	ds_read_b128 v[214:217], v142 offset:3072
	ds_read_b128 v[218:221], v142 offset:4096
	ds_read_b128 v[222:225], v142 offset:5120
	ds_read_b128 v[226:229], v142 offset:6144
	ds_read_b128 v[230:233], v142 offset:7168
	global_load_lds_dwordx4 v[202:203], off
	v_lshl_add_u64 v[202:203], v[202:203], 0, s[72:73]
	s_add_i32 m0, s43, 0xe000
	s_nop 0
	global_load_lds_dwordx4 v[202:203], off
	s_waitcnt vmcnt(8)
	s_waitcnt lgkmcnt(0)
	s_barrier
	s_setprio 1
	s_waitcnt lgkmcnt(0)
	v_mfma_f32_16x16x32_bf16 v[126:129], v[134:137], v[190:193], v[126:129]
	v_mfma_f32_16x16x32_bf16 v[126:129], v[144:147], v[194:197], v[126:129]
	v_mfma_f32_16x16x32_bf16 v[114:117], v[148:151], v[190:193], v[114:117]
	v_mfma_f32_16x16x32_bf16 v[114:117], v[152:155], v[194:197], v[114:117]
	v_mfma_f32_16x16x32_bf16 v[110:113], v[134:137], v[198:201], v[110:113]
	v_mfma_f32_16x16x32_bf16 v[110:113], v[144:147], v[214:217], v[110:113]
	v_mfma_f32_16x16x32_bf16 v[98:101], v[148:151], v[198:201], v[98:101]
	v_mfma_f32_16x16x32_bf16 v[98:101], v[152:155], v[214:217], v[98:101]
	v_mfma_f32_16x16x32_bf16 v[94:97], v[134:137], v[218:221], v[94:97]
	v_mfma_f32_16x16x32_bf16 v[94:97], v[144:147], v[222:225], v[94:97]
	v_mfma_f32_16x16x32_bf16 v[82:85], v[148:151], v[218:221], v[82:85]
	v_mfma_f32_16x16x32_bf16 v[82:85], v[152:155], v[222:225], v[82:85]
	v_mfma_f32_16x16x32_bf16 v[78:81], v[134:137], v[226:229], v[78:81]
	v_mfma_f32_16x16x32_bf16 v[78:81], v[144:147], v[230:233], v[78:81]
	v_mfma_f32_16x16x32_bf16 v[66:69], v[148:151], v[226:229], v[66:69]
	v_mfma_f32_16x16x32_bf16 v[66:69], v[152:155], v[230:233], v[66:69]
	s_setprio 0
	s_setprio 1
	v_mfma_f32_16x16x32_bf16 v[122:125], v[156:159], v[190:193], v[122:125]
	v_mfma_f32_16x16x32_bf16 v[122:125], v[160:163], v[194:197], v[122:125]
	v_mfma_f32_16x16x32_bf16 v[118:121], v[182:185], v[190:193], v[118:121]
	v_mfma_f32_16x16x32_bf16 v[118:121], v[186:189], v[194:197], v[118:121]
	v_mfma_f32_16x16x32_bf16 v[106:109], v[156:159], v[198:201], v[106:109]
	v_mfma_f32_16x16x32_bf16 v[106:109], v[160:163], v[214:217], v[106:109]
	v_mfma_f32_16x16x32_bf16 v[102:105], v[182:185], v[198:201], v[102:105]
	v_mfma_f32_16x16x32_bf16 v[102:105], v[186:189], v[214:217], v[102:105]
	v_mfma_f32_16x16x32_bf16 v[90:93], v[156:159], v[218:221], v[90:93]
	v_mfma_f32_16x16x32_bf16 v[90:93], v[160:163], v[222:225], v[90:93]
	v_mfma_f32_16x16x32_bf16 v[86:89], v[182:185], v[218:221], v[86:89]
	v_mfma_f32_16x16x32_bf16 v[86:89], v[186:189], v[222:225], v[86:89]
	v_mfma_f32_16x16x32_bf16 v[74:77], v[156:159], v[226:229], v[74:77]
	v_mfma_f32_16x16x32_bf16 v[74:77], v[160:163], v[230:233], v[74:77]
	v_mfma_f32_16x16x32_bf16 v[70:73], v[182:185], v[226:229], v[70:73]
	v_mfma_f32_16x16x32_bf16 v[70:73], v[186:189], v[230:233], v[70:73]
	s_setprio 0
	s_barrier
	v_lshl_add_u64 v[202:203], s[20:21], 0, v[0:1]
	s_add_i32 s20, s22, s14
	s_mov_b32 m0, s20
	ds_read_b128 v[190:193], v142 offset:16384
	ds_read_b128 v[194:197], v142 offset:17408
	ds_read_b128 v[198:201], v142 offset:18432
	ds_read_b128 v[214:217], v142 offset:19456
	ds_read_b128 v[218:221], v142 offset:20480
	ds_read_b128 v[222:225], v142 offset:21504
	ds_read_b128 v[226:229], v142 offset:22528
	ds_read_b128 v[230:233], v142 offset:23552
	global_load_lds_dwordx4 v[202:203], off
	v_lshl_add_u64 v[234:235], v[202:203], 0, s[72:73]
	s_add_i32 m0, s20, 0x2000
	s_add_i32 s20, s23, s14
	global_load_lds_dwordx4 v[234:235], off
	v_lshl_add_u64 v[234:235], v[202:203], 0, s[28:29]
	s_mov_b32 m0, s20
	s_nop 0
	global_load_lds_dwordx4 v[234:235], off
	v_lshl_add_u64 v[234:235], v[202:203], 0, s[82:83]
	s_add_i32 m0, s20, 0x2000
	s_nop 0
	global_load_lds_dwordx4 v[234:235], off
	v_lshl_add_u64 v[234:235], s[76:77], 0, v[130:131]
	s_mov_b32 m0, s43
	v_lshl_add_u64 v[236:237], v[234:235], 0, s[72:73]
	global_load_lds_dwordx4 v[234:235], off
	s_mov_b32 m0, s46
	s_nop 0
	global_load_lds_dwordx4 v[236:237], off
	s_waitcnt vmcnt(8)
	s_waitcnt lgkmcnt(0)
	s_barrier
	s_setprio 1
	s_waitcnt lgkmcnt(0)
	v_mfma_f32_16x16x32_bf16 v[62:65], v[134:137], v[190:193], v[62:65]
	v_mfma_f32_16x16x32_bf16 v[62:65], v[144:147], v[194:197], v[62:65]
	v_mfma_f32_16x16x32_bf16 v[50:53], v[148:151], v[190:193], v[50:53]
	v_mfma_f32_16x16x32_bf16 v[50:53], v[152:155], v[194:197], v[50:53]
	v_mfma_f32_16x16x32_bf16 v[46:49], v[134:137], v[198:201], v[46:49]
	v_mfma_f32_16x16x32_bf16 v[46:49], v[144:147], v[214:217], v[46:49]
	v_mfma_f32_16x16x32_bf16 v[34:37], v[148:151], v[198:201], v[34:37]
	v_mfma_f32_16x16x32_bf16 v[34:37], v[152:155], v[214:217], v[34:37]
	v_mfma_f32_16x16x32_bf16 v[30:33], v[134:137], v[218:221], v[30:33]
	v_mfma_f32_16x16x32_bf16 v[30:33], v[144:147], v[222:225], v[30:33]
	v_mfma_f32_16x16x32_bf16 v[18:21], v[148:151], v[218:221], v[18:21]
	v_mfma_f32_16x16x32_bf16 v[18:21], v[152:155], v[222:225], v[18:21]
	v_mfma_f32_16x16x32_bf16 v[14:17], v[134:137], v[226:229], v[14:17]
	v_mfma_f32_16x16x32_bf16 v[14:17], v[144:147], v[230:233], v[14:17]
	v_mfma_f32_16x16x32_bf16 v[6:9], v[148:151], v[226:229], v[6:9]
	v_mfma_f32_16x16x32_bf16 v[6:9], v[152:155], v[230:233], v[6:9]
	s_setprio 0
	s_setprio 1
	v_mfma_f32_16x16x32_bf16 v[58:61], v[156:159], v[190:193], v[58:61]
	v_mfma_f32_16x16x32_bf16 v[58:61], v[160:163], v[194:197], v[58:61]
	v_mfma_f32_16x16x32_bf16 v[54:57], v[182:185], v[190:193], v[54:57]
	v_mfma_f32_16x16x32_bf16 v[54:57], v[186:189], v[194:197], v[54:57]
	v_mfma_f32_16x16x32_bf16 v[42:45], v[156:159], v[198:201], v[42:45]
	v_mfma_f32_16x16x32_bf16 v[42:45], v[160:163], v[214:217], v[42:45]
	v_mfma_f32_16x16x32_bf16 v[38:41], v[182:185], v[198:201], v[38:41]
	v_mfma_f32_16x16x32_bf16 v[38:41], v[186:189], v[214:217], v[38:41]
	v_mfma_f32_16x16x32_bf16 v[26:29], v[156:159], v[218:221], v[26:29]
	v_mfma_f32_16x16x32_bf16 v[26:29], v[160:163], v[222:225], v[26:29]
	v_mfma_f32_16x16x32_bf16 v[22:25], v[182:185], v[218:221], v[22:25]
	v_mfma_f32_16x16x32_bf16 v[22:25], v[186:189], v[222:225], v[22:25]
	v_mfma_f32_16x16x32_bf16 v[10:13], v[156:159], v[226:229], v[10:13]
	v_mfma_f32_16x16x32_bf16 v[10:13], v[160:163], v[230:233], v[10:13]
	v_mfma_f32_16x16x32_bf16 v[2:5], v[182:185], v[226:229], v[2:5]
	v_mfma_f32_16x16x32_bf16 v[2:5], v[186:189], v[230:233], v[2:5]
	s_setprio 0
	s_barrier
	s_add_i32 s20, 0, 0x18000
	v_add_u32_e32 v143, s20, v139
	s_add_i32 s21, 0, 0x1c000
	ds_read_b128 v[134:137], v143
	ds_read_b128 v[144:147], v143 offset:1024
	ds_read_b128 v[148:151], v143 offset:2048
	ds_read_b128 v[152:155], v143 offset:3072
	v_add_u32_e32 v143, s21, v139
	ds_read_b128 v[156:159], v143
	ds_read_b128 v[160:163], v143 offset:1024
	ds_read_b128 v[182:185], v143 offset:2048
	ds_read_b128 v[186:189], v143 offset:3072
	s_mov_b32 m0, s47
	v_lshl_add_u64 v[236:237], v[234:235], 0, s[28:29]
	ds_read_b128 v[190:193], v142 offset:32768
	ds_read_b128 v[194:197], v142 offset:33792
	ds_read_b128 v[198:201], v142 offset:34816
	ds_read_b128 v[214:217], v142 offset:35840
	ds_read_b128 v[218:221], v142 offset:36864
	ds_read_b128 v[222:225], v142 offset:37888
	ds_read_b128 v[226:229], v142 offset:38912
	ds_read_b128 v[230:233], v142 offset:39936
	global_load_lds_dwordx4 v[236:237], off
	v_lshl_add_u64 v[236:237], v[234:235], 0, s[82:83]
	s_mov_b32 m0, s78
	s_nop 0
	global_load_lds_dwordx4 v[236:237], off
	s_waitcnt vmcnt(8)
	s_waitcnt lgkmcnt(0)
	s_barrier
	s_setprio 1
	s_waitcnt lgkmcnt(0)
	v_mfma_f32_16x16x32_bf16 v[126:129], v[134:137], v[190:193], v[126:129]
	v_mfma_f32_16x16x32_bf16 v[126:129], v[144:147], v[194:197], v[126:129]
	v_mfma_f32_16x16x32_bf16 v[114:117], v[148:151], v[190:193], v[114:117]
	v_mfma_f32_16x16x32_bf16 v[114:117], v[152:155], v[194:197], v[114:117]
	v_mfma_f32_16x16x32_bf16 v[110:113], v[134:137], v[198:201], v[110:113]
	v_mfma_f32_16x16x32_bf16 v[110:113], v[144:147], v[214:217], v[110:113]
	v_mfma_f32_16x16x32_bf16 v[98:101], v[148:151], v[198:201], v[98:101]
	v_mfma_f32_16x16x32_bf16 v[98:101], v[152:155], v[214:217], v[98:101]
	v_mfma_f32_16x16x32_bf16 v[94:97], v[134:137], v[218:221], v[94:97]
	v_mfma_f32_16x16x32_bf16 v[94:97], v[144:147], v[222:225], v[94:97]
	v_mfma_f32_16x16x32_bf16 v[82:85], v[148:151], v[218:221], v[82:85]
	v_mfma_f32_16x16x32_bf16 v[82:85], v[152:155], v[222:225], v[82:85]
	v_mfma_f32_16x16x32_bf16 v[78:81], v[134:137], v[226:229], v[78:81]
	v_mfma_f32_16x16x32_bf16 v[78:81], v[144:147], v[230:233], v[78:81]
	v_mfma_f32_16x16x32_bf16 v[66:69], v[148:151], v[226:229], v[66:69]
	v_mfma_f32_16x16x32_bf16 v[66:69], v[152:155], v[230:233], v[66:69]
	s_setprio 0
	s_setprio 1
	v_mfma_f32_16x16x32_bf16 v[122:125], v[156:159], v[190:193], v[122:125]
	v_mfma_f32_16x16x32_bf16 v[122:125], v[160:163], v[194:197], v[122:125]
	v_mfma_f32_16x16x32_bf16 v[118:121], v[182:185], v[190:193], v[118:121]
	v_mfma_f32_16x16x32_bf16 v[118:121], v[186:189], v[194:197], v[118:121]
	v_mfma_f32_16x16x32_bf16 v[106:109], v[156:159], v[198:201], v[106:109]
	v_mfma_f32_16x16x32_bf16 v[106:109], v[160:163], v[214:217], v[106:109]
	v_mfma_f32_16x16x32_bf16 v[102:105], v[182:185], v[198:201], v[102:105]
	v_mfma_f32_16x16x32_bf16 v[102:105], v[186:189], v[214:217], v[102:105]
	v_mfma_f32_16x16x32_bf16 v[90:93], v[156:159], v[218:221], v[90:93]
	v_mfma_f32_16x16x32_bf16 v[90:93], v[160:163], v[222:225], v[90:93]
	v_mfma_f32_16x16x32_bf16 v[86:89], v[182:185], v[218:221], v[86:89]
	v_mfma_f32_16x16x32_bf16 v[86:89], v[186:189], v[222:225], v[86:89]
	v_mfma_f32_16x16x32_bf16 v[74:77], v[156:159], v[226:229], v[74:77]
	v_mfma_f32_16x16x32_bf16 v[74:77], v[160:163], v[230:233], v[74:77]
	v_mfma_f32_16x16x32_bf16 v[70:73], v[182:185], v[226:229], v[70:73]
	v_mfma_f32_16x16x32_bf16 v[70:73], v[186:189], v[230:233], v[70:73]
	s_setprio 0
	s_barrier
	s_add_i32 s20, s20, s14
	v_lshl_add_u64 v[236:237], v[202:203], 0, s[34:35]
	s_mov_b32 m0, s20
	ds_read_b128 v[190:193], v142 offset:49152
	ds_read_b128 v[194:197], v142 offset:50176
	ds_read_b128 v[198:201], v142 offset:51200
	ds_read_b128 v[214:217], v142 offset:52224
	ds_read_b128 v[218:221], v142 offset:53248
	ds_read_b128 v[222:225], v142 offset:54272
	ds_read_b128 v[226:229], v142 offset:55296
	ds_read_b128 v[230:233], v142 offset:56320
	global_load_lds_dwordx4 v[236:237], off
	v_lshl_add_u64 v[236:237], v[202:203], 0, s[38:39]
	s_add_i32 m0, s20, 0x2000
	s_add_i32 s20, s21, s14
	global_load_lds_dwordx4 v[236:237], off
	v_lshl_add_u64 v[236:237], v[202:203], 0, s[44:45]
	s_mov_b32 m0, s20
	v_lshl_add_u64 v[202:203], v[202:203], 0, s[10:11]
	global_load_lds_dwordx4 v[236:237], off
	s_add_i32 m0, s20, 0x2000
	s_nop 0
	global_load_lds_dwordx4 v[202:203], off
	v_lshl_add_u64 v[202:203], v[234:235], 0, s[34:35]
	s_mov_b32 m0, s79
	s_nop 0
	global_load_lds_dwordx4 v[202:203], off
	v_lshl_add_u64 v[202:203], v[234:235], 0, s[38:39]
	s_mov_b32 m0, s88
	s_nop 0
	global_load_lds_dwordx4 v[202:203], off
	s_waitcnt vmcnt(8)
	s_waitcnt lgkmcnt(0)
	s_barrier
	s_setprio 1
	s_waitcnt lgkmcnt(0)
	v_mfma_f32_16x16x32_bf16 v[62:65], v[134:137], v[190:193], v[62:65]
	v_mfma_f32_16x16x32_bf16 v[62:65], v[144:147], v[194:197], v[62:65]
	v_mfma_f32_16x16x32_bf16 v[50:53], v[148:151], v[190:193], v[50:53]
	v_mfma_f32_16x16x32_bf16 v[50:53], v[152:155], v[194:197], v[50:53]
	v_mfma_f32_16x16x32_bf16 v[46:49], v[134:137], v[198:201], v[46:49]
	v_mfma_f32_16x16x32_bf16 v[46:49], v[144:147], v[214:217], v[46:49]
	v_mfma_f32_16x16x32_bf16 v[34:37], v[148:151], v[198:201], v[34:37]
	v_mfma_f32_16x16x32_bf16 v[34:37], v[152:155], v[214:217], v[34:37]
	v_mfma_f32_16x16x32_bf16 v[30:33], v[134:137], v[218:221], v[30:33]
	v_mfma_f32_16x16x32_bf16 v[30:33], v[144:147], v[222:225], v[30:33]
	v_mfma_f32_16x16x32_bf16 v[18:21], v[148:151], v[218:221], v[18:21]
	v_mfma_f32_16x16x32_bf16 v[18:21], v[152:155], v[222:225], v[18:21]
	v_mfma_f32_16x16x32_bf16 v[14:17], v[134:137], v[226:229], v[14:17]
	v_mfma_f32_16x16x32_bf16 v[14:17], v[144:147], v[230:233], v[14:17]
	v_mfma_f32_16x16x32_bf16 v[6:9], v[148:151], v[226:229], v[6:9]
	v_mfma_f32_16x16x32_bf16 v[6:9], v[152:155], v[230:233], v[6:9]
	s_setprio 0
	s_setprio 1
	v_mfma_f32_16x16x32_bf16 v[58:61], v[156:159], v[190:193], v[58:61]
	v_mfma_f32_16x16x32_bf16 v[58:61], v[160:163], v[194:197], v[58:61]
	v_mfma_f32_16x16x32_bf16 v[54:57], v[182:185], v[190:193], v[54:57]
	v_mfma_f32_16x16x32_bf16 v[54:57], v[186:189], v[194:197], v[54:57]
	v_mfma_f32_16x16x32_bf16 v[42:45], v[156:159], v[198:201], v[42:45]
	v_mfma_f32_16x16x32_bf16 v[42:45], v[160:163], v[214:217], v[42:45]
	v_mfma_f32_16x16x32_bf16 v[38:41], v[182:185], v[198:201], v[38:41]
	v_mfma_f32_16x16x32_bf16 v[38:41], v[186:189], v[214:217], v[38:41]
	v_mfma_f32_16x16x32_bf16 v[26:29], v[156:159], v[218:221], v[26:29]
	v_mfma_f32_16x16x32_bf16 v[26:29], v[160:163], v[222:225], v[26:29]
	v_mfma_f32_16x16x32_bf16 v[22:25], v[182:185], v[218:221], v[22:25]
	v_mfma_f32_16x16x32_bf16 v[22:25], v[186:189], v[222:225], v[22:25]
	v_mfma_f32_16x16x32_bf16 v[10:13], v[156:159], v[226:229], v[10:13]
	v_mfma_f32_16x16x32_bf16 v[10:13], v[160:163], v[230:233], v[10:13]
	v_mfma_f32_16x16x32_bf16 v[2:5], v[182:185], v[226:229], v[2:5]
	v_mfma_f32_16x16x32_bf16 v[2:5], v[186:189], v[230:233], v[2:5]
	s_setprio 0
	s_barrier
	s_add_i32 s97, s97, 2
	s_add_u32 s68, s68, 0x100
	s_addc_u32 s69, s69, 0
	s_add_u32 s91, s91, 0x100
	s_addc_u32 s96, s96, 0
	s_cmp_gt_u32 s97, 13
	s_cbranch_scc0 .LBB0_488
	s_and_b64 vcc, exec, s[48:49]
	s_cbranch_vccz .LBB0_491
	s_barrier

.LBB0_562:
	s_add_u32 s20, s62, s68
	s_addc_u32 s21, s63, s69
	s_add_u32 s20, s20, 0x100
	s_addc_u32 s21, s21, 0
	s_add_u32 s22, s97, s68
	s_addc_u32 s23, vcc_lo, s69
	s_cmpk_eq_i32 s68, 0x700
	s_cselect_b32 s77, s51, s21
	s_cselect_b32 s76, s86, s20
	s_cselect_b32 s21, s49, s23
	s_cselect_b32 s20, s87, s22
	s_add_i32 s22, 0, 0x10000
	v_add_u32_e32 v0, s22, v215
	s_add_i32 s23, 0, 0x14000
	ds_read_b128 v[118:121], v0
	ds_read_b128 v[122:125], v0 offset:1024
	ds_read_b128 v[132:135], v0 offset:2048
	ds_read_b128 v[148:151], v0 offset:3072
	v_add_u32_e32 v0, s23, v215
	ds_read_b128 v[152:155], v0
	ds_read_b128 v[156:159], v0 offset:1024
	ds_read_b128 v[160:163], v0 offset:2048
	ds_read_b128 v[188:191], v0 offset:3072
	v_lshl_add_u64 v[2:3], v[116:117], 0, s[68:69]
	v_lshl_add_u64 v[126:127], v[2:3], 0, s[44:45]
	s_add_i32 m0, s47, 0xc000
	ds_read_b128 v[192:195], v218
	ds_read_b128 v[196:199], v218 offset:1024
	ds_read_b128 v[200:203], v218 offset:2048
	ds_read_b128 v[220:223], v218 offset:3072
	ds_read_b128 v[224:227], v218 offset:4096
	ds_read_b128 v[228:231], v218 offset:5120
	ds_read_b128 v[232:235], v218 offset:6144
	ds_read_b128 v[236:239], v218 offset:7168
	global_load_lds_dwordx4 v[126:127], off
	v_lshl_add_u64 v[2:3], v[2:3], 0, s[10:11]
	s_add_i32 m0, s47, 0xe000
	s_nop 0
	global_load_lds_dwordx4 v[2:3], off
	s_waitcnt vmcnt(8)
	s_waitcnt lgkmcnt(0)
	s_barrier
	s_setprio 1
	s_waitcnt lgkmcnt(0)
	v_mfma_f32_16x16x32_bf16 v[144:147], v[118:121], v[192:195], v[144:147]
	v_mfma_f32_16x16x32_bf16 v[144:147], v[122:125], v[196:199], v[144:147]
	v_mfma_f32_16x16x32_bf16 v[140:143], v[132:135], v[192:195], v[140:143]
	v_mfma_f32_16x16x32_bf16 v[140:143], v[148:151], v[196:199], v[140:143]
	v_mfma_f32_16x16x32_bf16 v[112:115], v[118:121], v[200:203], v[112:115]
	v_mfma_f32_16x16x32_bf16 v[112:115], v[122:125], v[220:223], v[112:115]
	v_mfma_f32_16x16x32_bf16 v[108:111], v[132:135], v[200:203], v[108:111]
	v_mfma_f32_16x16x32_bf16 v[108:111], v[148:151], v[220:223], v[108:111]
	v_mfma_f32_16x16x32_bf16 v[96:99], v[118:121], v[224:227], v[96:99]
	v_mfma_f32_16x16x32_bf16 v[96:99], v[122:125], v[228:231], v[96:99]
	v_mfma_f32_16x16x32_bf16 v[92:95], v[132:135], v[224:227], v[92:95]
	v_mfma_f32_16x16x32_bf16 v[92:95], v[148:151], v[228:231], v[92:95]
	v_mfma_f32_16x16x32_bf16 v[80:83], v[118:121], v[232:235], v[80:83]
	v_mfma_f32_16x16x32_bf16 v[80:83], v[122:125], v[236:239], v[80:83]
	v_mfma_f32_16x16x32_bf16 v[76:79], v[132:135], v[232:235], v[76:79]
	v_mfma_f32_16x16x32_bf16 v[76:79], v[148:151], v[236:239], v[76:79]
	s_setprio 0
	s_setprio 1
	v_mfma_f32_16x16x32_bf16 v[136:139], v[152:155], v[192:195], v[136:139]
	v_mfma_f32_16x16x32_bf16 v[136:139], v[156:159], v[196:199], v[136:139]
	v_mfma_f32_16x16x32_bf16 v[126:129], v[160:163], v[192:195], v[128:131]
	v_mfma_f32_16x16x32_bf16 v[126:129], v[188:191], v[196:199], v[126:129]
	v_mfma_f32_16x16x32_bf16 v[104:107], v[152:155], v[200:203], v[104:107]
	v_mfma_f32_16x16x32_bf16 v[104:107], v[156:159], v[220:223], v[104:107]
	v_mfma_f32_16x16x32_bf16 v[100:103], v[160:163], v[200:203], v[100:103]
	v_mfma_f32_16x16x32_bf16 v[100:103], v[188:191], v[220:223], v[100:103]
	v_mfma_f32_16x16x32_bf16 v[88:91], v[152:155], v[224:227], v[88:91]
	v_mfma_f32_16x16x32_bf16 v[88:91], v[156:159], v[228:231], v[88:91]
	v_mfma_f32_16x16x32_bf16 v[84:87], v[160:163], v[224:227], v[84:87]
	v_mfma_f32_16x16x32_bf16 v[84:87], v[188:191], v[228:231], v[84:87]
	v_mfma_f32_16x16x32_bf16 v[72:75], v[152:155], v[232:235], v[72:75]
	v_mfma_f32_16x16x32_bf16 v[72:75], v[156:159], v[236:239], v[72:75]
	v_mfma_f32_16x16x32_bf16 v[68:71], v[160:163], v[232:235], v[68:71]
	v_mfma_f32_16x16x32_bf16 v[68:71], v[188:191], v[236:239], v[68:71]
	s_setprio 0
	s_barrier
	v_lshl_add_u64 v[240:241], s[20:21], 0, v[182:183]
	s_add_i32 s20, s22, s14
	s_mov_b32 m0, s20
	ds_read_b128 v[192:195], v218 offset:16384
	ds_read_b128 v[196:199], v218 offset:17408
	ds_read_b128 v[200:203], v218 offset:18432
	ds_read_b128 v[220:223], v218 offset:19456
	ds_read_b128 v[224:227], v218 offset:20480
	ds_read_b128 v[228:231], v218 offset:21504
	ds_read_b128 v[232:235], v218 offset:22528
	ds_read_b128 v[236:239], v218 offset:23552
	global_load_lds_dwordx4 v[240:241], off
	v_lshl_add_u64 v[2:3], v[240:241], 0, s[72:73]
	s_add_i32 m0, s20, 0x2000
	s_add_i32 s20, s23, s14
	global_load_lds_dwordx4 v[2:3], off
	v_lshl_add_u64 v[2:3], v[240:241], 0, s[28:29]
	s_mov_b32 m0, s20
	v_lshl_add_u64 v[242:243], s[76:77], 0, v[184:185]
	global_load_lds_dwordx4 v[2:3], off
	v_lshl_add_u64 v[2:3], v[240:241], 0, s[82:83]
	s_add_i32 m0, s20, 0x2000
	s_nop 0
	global_load_lds_dwordx4 v[2:3], off
	s_mov_b32 m0, s47
	v_lshl_add_u64 v[2:3], v[242:243], 0, s[72:73]
	global_load_lds_dwordx4 v[242:243], off
	s_mov_b32 m0, s79
	s_nop 0
	global_load_lds_dwordx4 v[2:3], off
	s_waitcnt vmcnt(8)
	s_waitcnt lgkmcnt(0)
	s_barrier
	s_setprio 1
	s_waitcnt lgkmcnt(0)
	v_mfma_f32_16x16x32_bf16 v[64:67], v[118:121], v[192:195], v[64:67]
	v_mfma_f32_16x16x32_bf16 v[64:67], v[122:125], v[196:199], v[64:67]
	v_mfma_f32_16x16x32_bf16 v[60:63], v[132:135], v[192:195], v[60:63]
	v_mfma_f32_16x16x32_bf16 v[60:63], v[148:151], v[196:199], v[60:63]
	v_mfma_f32_16x16x32_bf16 v[48:51], v[118:121], v[200:203], v[48:51]
	v_mfma_f32_16x16x32_bf16 v[48:51], v[122:125], v[220:223], v[48:51]
	v_mfma_f32_16x16x32_bf16 v[44:47], v[132:135], v[200:203], v[44:47]
	v_mfma_f32_16x16x32_bf16 v[44:47], v[148:151], v[220:223], v[44:47]
	v_mfma_f32_16x16x32_bf16 v[32:35], v[118:121], v[224:227], v[32:35]
	v_mfma_f32_16x16x32_bf16 v[32:35], v[122:125], v[228:231], v[32:35]
	v_mfma_f32_16x16x32_bf16 v[28:31], v[132:135], v[224:227], v[28:31]
	v_mfma_f32_16x16x32_bf16 v[28:31], v[148:151], v[228:231], v[28:31]
	v_mfma_f32_16x16x32_bf16 v[16:19], v[118:121], v[232:235], v[16:19]
	v_mfma_f32_16x16x32_bf16 v[16:19], v[122:125], v[236:239], v[16:19]
	v_mfma_f32_16x16x32_bf16 v[12:15], v[132:135], v[232:235], v[12:15]
	v_mfma_f32_16x16x32_bf16 v[12:15], v[148:151], v[236:239], v[12:15]
	s_setprio 0
	s_setprio 1
	v_mfma_f32_16x16x32_bf16 v[56:59], v[152:155], v[192:195], v[56:59]
	v_mfma_f32_16x16x32_bf16 v[56:59], v[156:159], v[196:199], v[56:59]
	v_mfma_f32_16x16x32_bf16 v[52:55], v[160:163], v[192:195], v[52:55]
	v_mfma_f32_16x16x32_bf16 v[52:55], v[188:191], v[196:199], v[52:55]
	v_mfma_f32_16x16x32_bf16 v[40:43], v[152:155], v[200:203], v[40:43]
	v_mfma_f32_16x16x32_bf16 v[40:43], v[156:159], v[220:223], v[40:43]
	v_mfma_f32_16x16x32_bf16 v[36:39], v[160:163], v[200:203], v[36:39]
	v_mfma_f32_16x16x32_bf16 v[36:39], v[188:191], v[220:223], v[36:39]
	v_mfma_f32_16x16x32_bf16 v[24:27], v[152:155], v[224:227], v[24:27]
	v_mfma_f32_16x16x32_bf16 v[24:27], v[156:159], v[228:231], v[24:27]
	v_mfma_f32_16x16x32_bf16 v[20:23], v[160:163], v[224:227], v[20:23]
	v_mfma_f32_16x16x32_bf16 v[20:23], v[188:191], v[228:231], v[20:23]
	v_mfma_f32_16x16x32_bf16 v[8:11], v[152:155], v[232:235], v[8:11]
	v_mfma_f32_16x16x32_bf16 v[8:11], v[156:159], v[236:239], v[8:11]
	v_mfma_f32_16x16x32_bf16 v[2:5], v[160:163], v[232:235], v[4:7]
	v_mfma_f32_16x16x32_bf16 v[2:5], v[188:191], v[236:239], v[2:5]
	s_setprio 0
	s_barrier
	s_add_i32 s20, 0, 0x18000
	v_add_u32_e32 v0, s20, v215
	s_add_i32 s21, 0, 0x1c000
	ds_read_b128 v[118:121], v0
	ds_read_b128 v[122:125], v0 offset:1024
	ds_read_b128 v[132:135], v0 offset:2048
	ds_read_b128 v[148:151], v0 offset:3072
	v_add_u32_e32 v0, s21, v215
	ds_read_b128 v[152:155], v0
	ds_read_b128 v[156:159], v0 offset:1024
	ds_read_b128 v[160:163], v0 offset:2048
	ds_read_b128 v[188:191], v0 offset:3072
	s_mov_b32 m0, s88
	v_lshl_add_u64 v[6:7], v[242:243], 0, s[28:29]
	ds_read_b128 v[192:195], v218 offset:32768
	ds_read_b128 v[196:199], v218 offset:33792
	ds_read_b128 v[200:203], v218 offset:34816
	ds_read_b128 v[220:223], v218 offset:35840
	ds_read_b128 v[224:227], v218 offset:36864
	ds_read_b128 v[228:231], v218 offset:37888
	ds_read_b128 v[232:235], v218 offset:38912
	ds_read_b128 v[236:239], v218 offset:39936
	global_load_lds_dwordx4 v[6:7], off
	v_lshl_add_u64 v[6:7], v[242:243], 0, s[82:83]
	s_mov_b32 m0, s89
	s_nop 0
	global_load_lds_dwordx4 v[6:7], off
	s_waitcnt vmcnt(8)
	s_waitcnt lgkmcnt(0)
	s_barrier
	s_setprio 1
	s_waitcnt lgkmcnt(0)
	v_mfma_f32_16x16x32_bf16 v[144:147], v[118:121], v[192:195], v[144:147]
	v_mfma_f32_16x16x32_bf16 v[144:147], v[122:125], v[196:199], v[144:147]
	v_mfma_f32_16x16x32_bf16 v[140:143], v[132:135], v[192:195], v[140:143]
	v_mfma_f32_16x16x32_bf16 v[140:143], v[148:151], v[196:199], v[140:143]
	v_mfma_f32_16x16x32_bf16 v[112:115], v[118:121], v[200:203], v[112:115]
	v_mfma_f32_16x16x32_bf16 v[112:115], v[122:125], v[220:223], v[112:115]
	v_mfma_f32_16x16x32_bf16 v[108:111], v[132:135], v[200:203], v[108:111]
	v_mfma_f32_16x16x32_bf16 v[108:111], v[148:151], v[220:223], v[108:111]
	v_mfma_f32_16x16x32_bf16 v[96:99], v[118:121], v[224:227], v[96:99]
	v_mfma_f32_16x16x32_bf16 v[96:99], v[122:125], v[228:231], v[96:99]
	v_mfma_f32_16x16x32_bf16 v[92:95], v[132:135], v[224:227], v[92:95]
	v_mfma_f32_16x16x32_bf16 v[92:95], v[148:151], v[228:231], v[92:95]
	v_mfma_f32_16x16x32_bf16 v[80:83], v[118:121], v[232:235], v[80:83]
	v_mfma_f32_16x16x32_bf16 v[80:83], v[122:125], v[236:239], v[80:83]
	v_mfma_f32_16x16x32_bf16 v[76:79], v[132:135], v[232:235], v[76:79]
	v_mfma_f32_16x16x32_bf16 v[76:79], v[148:151], v[236:239], v[76:79]
	s_setprio 0
	s_setprio 1
	v_mfma_f32_16x16x32_bf16 v[136:139], v[152:155], v[192:195], v[136:139]
	v_mfma_f32_16x16x32_bf16 v[136:139], v[156:159], v[196:199], v[136:139]
	v_mfma_f32_16x16x32_bf16 v[126:129], v[160:163], v[192:195], v[126:129]
	v_mfma_f32_16x16x32_bf16 v[104:107], v[152:155], v[200:203], v[104:107]
	v_mfma_f32_16x16x32_bf16 v[104:107], v[156:159], v[220:223], v[104:107]
	v_mfma_f32_16x16x32_bf16 v[100:103], v[160:163], v[200:203], v[100:103]
	v_mfma_f32_16x16x32_bf16 v[100:103], v[188:191], v[220:223], v[100:103]
	v_mfma_f32_16x16x32_bf16 v[88:91], v[152:155], v[224:227], v[88:91]
	v_mfma_f32_16x16x32_bf16 v[88:91], v[156:159], v[228:231], v[88:91]
	v_mfma_f32_16x16x32_bf16 v[84:87], v[160:163], v[224:227], v[84:87]
	v_mfma_f32_16x16x32_bf16 v[84:87], v[188:191], v[228:231], v[84:87]
	v_mfma_f32_16x16x32_bf16 v[72:75], v[152:155], v[232:235], v[72:75]
	v_mfma_f32_16x16x32_bf16 v[72:75], v[156:159], v[236:239], v[72:75]
	v_mfma_f32_16x16x32_bf16 v[68:71], v[160:163], v[232:235], v[68:71]
	v_mfma_f32_16x16x32_bf16 v[68:71], v[188:191], v[236:239], v[68:71]
	v_mfma_f32_16x16x32_bf16 v[128:131], v[188:191], v[196:199], v[126:129]
	s_setprio 0
	s_barrier
	s_add_i32 s20, s20, s14
	v_lshl_add_u64 v[6:7], v[240:241], 0, s[34:35]
	s_mov_b32 m0, s20
	ds_read_b128 v[192:195], v218 offset:49152
	ds_read_b128 v[196:199], v218 offset:50176
	ds_read_b128 v[200:203], v218 offset:51200
	ds_read_b128 v[220:223], v218 offset:52224
	ds_read_b128 v[224:227], v218 offset:53248
	ds_read_b128 v[228:231], v218 offset:54272
	ds_read_b128 v[232:235], v218 offset:55296
	ds_read_b128 v[236:239], v218 offset:56320
	global_load_lds_dwordx4 v[6:7], off
	v_lshl_add_u64 v[6:7], v[240:241], 0, s[38:39]
	s_add_i32 m0, s20, 0x2000
	s_add_i32 s20, s21, s14
	global_load_lds_dwordx4 v[6:7], off
	v_lshl_add_u64 v[6:7], v[240:241], 0, s[44:45]
	s_mov_b32 m0, s20
	s_nop 0
	global_load_lds_dwordx4 v[6:7], off
	v_lshl_add_u64 v[6:7], v[240:241], 0, s[10:11]
	s_add_i32 m0, s20, 0x2000
	s_nop 0
	global_load_lds_dwordx4 v[6:7], off
	v_lshl_add_u64 v[6:7], v[242:243], 0, s[34:35]
	s_mov_b32 m0, s90
	s_nop 0
	global_load_lds_dwordx4 v[6:7], off
	v_lshl_add_u64 v[6:7], v[242:243], 0, s[38:39]
	s_mov_b32 m0, s91
	s_nop 0
	global_load_lds_dwordx4 v[6:7], off
	s_waitcnt vmcnt(8)
	s_waitcnt lgkmcnt(0)
	s_barrier
	s_setprio 1
	s_waitcnt lgkmcnt(0)
	v_mfma_f32_16x16x32_bf16 v[64:67], v[118:121], v[192:195], v[64:67]
	v_mfma_f32_16x16x32_bf16 v[64:67], v[122:125], v[196:199], v[64:67]
	v_mfma_f32_16x16x32_bf16 v[60:63], v[132:135], v[192:195], v[60:63]
	v_mfma_f32_16x16x32_bf16 v[60:63], v[148:151], v[196:199], v[60:63]
	v_mfma_f32_16x16x32_bf16 v[48:51], v[118:121], v[200:203], v[48:51]
	v_mfma_f32_16x16x32_bf16 v[48:51], v[122:125], v[220:223], v[48:51]
	v_mfma_f32_16x16x32_bf16 v[44:47], v[132:135], v[200:203], v[44:47]
	v_mfma_f32_16x16x32_bf16 v[44:47], v[148:151], v[220:223], v[44:47]
	v_mfma_f32_16x16x32_bf16 v[32:35], v[118:121], v[224:227], v[32:35]
	v_mfma_f32_16x16x32_bf16 v[32:35], v[122:125], v[228:231], v[32:35]
	v_mfma_f32_16x16x32_bf16 v[28:31], v[132:135], v[224:227], v[28:31]
	v_mfma_f32_16x16x32_bf16 v[28:31], v[148:151], v[228:231], v[28:31]
	v_mfma_f32_16x16x32_bf16 v[16:19], v[118:121], v[232:235], v[16:19]
	v_mfma_f32_16x16x32_bf16 v[16:19], v[122:125], v[236:239], v[16:19]
	v_mfma_f32_16x16x32_bf16 v[12:15], v[132:135], v[232:235], v[12:15]
	v_mfma_f32_16x16x32_bf16 v[12:15], v[148:151], v[236:239], v[12:15]
	s_setprio 0
	s_setprio 1
	v_mfma_f32_16x16x32_bf16 v[56:59], v[152:155], v[192:195], v[56:59]
	v_mfma_f32_16x16x32_bf16 v[56:59], v[156:159], v[196:199], v[56:59]
	v_mfma_f32_16x16x32_bf16 v[52:55], v[160:163], v[192:195], v[52:55]
	v_mfma_f32_16x16x32_bf16 v[52:55], v[188:191], v[196:199], v[52:55]
	v_mfma_f32_16x16x32_bf16 v[40:43], v[152:155], v[200:203], v[40:43]
	v_mfma_f32_16x16x32_bf16 v[40:43], v[156:159], v[220:223], v[40:43]
	v_mfma_f32_16x16x32_bf16 v[36:39], v[160:163], v[200:203], v[36:39]
	v_mfma_f32_16x16x32_bf16 v[36:39], v[188:191], v[220:223], v[36:39]
	v_mfma_f32_16x16x32_bf16 v[24:27], v[152:155], v[224:227], v[24:27]
	v_mfma_f32_16x16x32_bf16 v[24:27], v[156:159], v[228:231], v[24:27]
	v_mfma_f32_16x16x32_bf16 v[20:23], v[160:163], v[224:227], v[20:23]
	v_mfma_f32_16x16x32_bf16 v[20:23], v[188:191], v[228:231], v[20:23]
	v_mfma_f32_16x16x32_bf16 v[6:9], v[152:155], v[232:235], v[8:11]
	v_mfma_f32_16x16x32_bf16 v[2:5], v[160:163], v[232:235], v[2:5]
	v_mfma_f32_16x16x32_bf16 v[8:11], v[156:159], v[236:239], v[6:9]
	v_mfma_f32_16x16x32_bf16 v[4:7], v[188:191], v[236:239], v[2:5]
	s_setprio 0
	s_barrier
	s_add_i32 vcc_hi, vcc_hi, 2
	s_add_u32 s68, s68, 0x100
	s_addc_u32 s69, s69, 0
	s_cmp_gt_u32 vcc_hi, 13
	s_cbranch_scc1 .LBB0_565

.LBB0_604:
	s_add_u32 s20, s6, 0xfffe0080
	s_addc_u32 s21, s7, -1
	s_add_i32 s22, 0, 0x10000
	s_cmp_eq_u32 s84, 4
	s_cselect_b32 s69, s42, s21
	s_cselect_b32 s68, s43, s20
	s_cselect_b32 s21, s46, s51
	s_cselect_b32 s20, s47, s49
	s_add_i32 s23, 0, 0x14000
	v_add_u32_e32 v150, s22, v139
	v_add_u32_e32 v162, s23, v139
	ds_read_b128 v[134:137], v150
	ds_read_b128 v[142:145], v150 offset:1024
	ds_read_b128 v[146:149], v150 offset:2048
	ds_read_b128 v[150:153], v150 offset:3072
	ds_read_b128 v[154:157], v162
	ds_read_b128 v[158:161], v162 offset:1024
	ds_read_b128 v[182:185], v162 offset:2048
	ds_read_b128 v[186:189], v162 offset:3072
	v_lshl_add_u64 v[162:163], s[6:7], 0, v[132:133]
	s_add_i32 m0, s89, 0xc000
	ds_read_b128 v[190:193], v141
	ds_read_b128 v[194:197], v141 offset:1024
	ds_read_b128 v[198:201], v141 offset:2048
	ds_read_b128 v[214:217], v141 offset:3072
	ds_read_b128 v[218:221], v141 offset:4096
	ds_read_b128 v[222:225], v141 offset:5120
	ds_read_b128 v[226:229], v141 offset:6144
	ds_read_b128 v[230:233], v141 offset:7168
	global_load_lds_dwordx4 v[162:163], off
	v_lshl_add_u64 v[162:163], v[162:163], 0, s[64:65]
	s_add_i32 m0, s89, 0xe000
	s_nop 0
	global_load_lds_dwordx4 v[162:163], off
	s_waitcnt vmcnt(8)
	s_waitcnt lgkmcnt(0)
	s_barrier
	s_setprio 1
	s_waitcnt lgkmcnt(0)
	v_mfma_f32_16x16x32_bf16 v[126:129], v[134:137], v[190:193], v[126:129]
	v_mfma_f32_16x16x32_bf16 v[126:129], v[142:145], v[194:197], v[126:129]
	v_mfma_f32_16x16x32_bf16 v[122:125], v[146:149], v[190:193], v[122:125]
	v_mfma_f32_16x16x32_bf16 v[122:125], v[150:153], v[194:197], v[122:125]
	v_mfma_f32_16x16x32_bf16 v[110:113], v[134:137], v[198:201], v[110:113]
	v_mfma_f32_16x16x32_bf16 v[110:113], v[142:145], v[214:217], v[110:113]
	v_mfma_f32_16x16x32_bf16 v[106:109], v[146:149], v[198:201], v[106:109]
	v_mfma_f32_16x16x32_bf16 v[106:109], v[150:153], v[214:217], v[106:109]
	v_mfma_f32_16x16x32_bf16 v[94:97], v[134:137], v[218:221], v[94:97]
	v_mfma_f32_16x16x32_bf16 v[94:97], v[142:145], v[222:225], v[94:97]
	v_mfma_f32_16x16x32_bf16 v[90:93], v[146:149], v[218:221], v[90:93]
	v_mfma_f32_16x16x32_bf16 v[90:93], v[150:153], v[222:225], v[90:93]
	v_mfma_f32_16x16x32_bf16 v[78:81], v[134:137], v[226:229], v[78:81]
	v_mfma_f32_16x16x32_bf16 v[78:81], v[142:145], v[230:233], v[78:81]
	v_mfma_f32_16x16x32_bf16 v[74:77], v[146:149], v[226:229], v[74:77]
	v_mfma_f32_16x16x32_bf16 v[74:77], v[150:153], v[230:233], v[74:77]
	s_setprio 0
	s_setprio 1
	v_mfma_f32_16x16x32_bf16 v[118:121], v[154:157], v[190:193], v[118:121]
	v_mfma_f32_16x16x32_bf16 v[118:121], v[158:161], v[194:197], v[118:121]
	v_mfma_f32_16x16x32_bf16 v[114:117], v[182:185], v[190:193], v[114:117]
	v_mfma_f32_16x16x32_bf16 v[114:117], v[186:189], v[194:197], v[114:117]
	v_mfma_f32_16x16x32_bf16 v[102:105], v[154:157], v[198:201], v[102:105]
	v_mfma_f32_16x16x32_bf16 v[102:105], v[158:161], v[214:217], v[102:105]
	v_mfma_f32_16x16x32_bf16 v[98:101], v[182:185], v[198:201], v[98:101]
	v_mfma_f32_16x16x32_bf16 v[98:101], v[186:189], v[214:217], v[98:101]
	v_mfma_f32_16x16x32_bf16 v[86:89], v[154:157], v[218:221], v[86:89]
	v_mfma_f32_16x16x32_bf16 v[86:89], v[158:161], v[222:225], v[86:89]
	v_mfma_f32_16x16x32_bf16 v[82:85], v[182:185], v[218:221], v[82:85]
	v_mfma_f32_16x16x32_bf16 v[82:85], v[186:189], v[222:225], v[82:85]
	v_mfma_f32_16x16x32_bf16 v[70:73], v[154:157], v[226:229], v[70:73]
	v_mfma_f32_16x16x32_bf16 v[70:73], v[158:161], v[230:233], v[70:73]
	v_mfma_f32_16x16x32_bf16 v[66:69], v[182:185], v[226:229], v[66:69]
	v_mfma_f32_16x16x32_bf16 v[66:69], v[186:189], v[230:233], v[66:69]
	s_setprio 0
	s_barrier
	v_lshl_add_u64 v[162:163], s[20:21], 0, v[0:1]
	s_add_i32 s20, s22, s88
	s_mov_b32 m0, s20
	ds_read_b128 v[190:193], v141 offset:16384
	ds_read_b128 v[194:197], v141 offset:17408
	ds_read_b128 v[198:201], v141 offset:18432
	ds_read_b128 v[214:217], v141 offset:19456
	ds_read_b128 v[218:221], v141 offset:20480
	ds_read_b128 v[222:225], v141 offset:21504
	ds_read_b128 v[226:229], v141 offset:22528
	ds_read_b128 v[230:233], v141 offset:23552
	global_load_lds_dwordx4 v[162:163], off
	v_lshl_add_u64 v[202:203], v[162:163], 0, s[64:65]
	s_add_i32 m0, s20, 0x2000
	s_add_i32 s20, s23, s88
	global_load_lds_dwordx4 v[202:203], off
	v_lshl_add_u64 v[202:203], v[162:163], 0, s[72:73]
	s_mov_b32 m0, s20
	s_nop 0
	global_load_lds_dwordx4 v[202:203], off
	v_lshl_add_u64 v[202:203], v[162:163], 0, s[74:75]
	s_add_i32 m0, s20, 0x2000
	s_nop 0
	global_load_lds_dwordx4 v[202:203], off
	v_lshl_add_u64 v[202:203], s[68:69], 0, v[130:131]
	s_mov_b32 m0, s89
	v_lshl_add_u64 v[234:235], v[202:203], 0, s[64:65]
	global_load_lds_dwordx4 v[202:203], off
	s_mov_b32 m0, s90
	s_nop 0
	global_load_lds_dwordx4 v[234:235], off
	s_waitcnt vmcnt(8)
	s_waitcnt lgkmcnt(0)
	s_barrier
	s_setprio 1
	s_waitcnt lgkmcnt(0)
	v_mfma_f32_16x16x32_bf16 v[62:65], v[134:137], v[190:193], v[62:65]
	v_mfma_f32_16x16x32_bf16 v[62:65], v[142:145], v[194:197], v[62:65]
	v_mfma_f32_16x16x32_bf16 v[58:61], v[146:149], v[190:193], v[58:61]
	v_mfma_f32_16x16x32_bf16 v[58:61], v[150:153], v[194:197], v[58:61]
	v_mfma_f32_16x16x32_bf16 v[46:49], v[134:137], v[198:201], v[46:49]
	v_mfma_f32_16x16x32_bf16 v[46:49], v[142:145], v[214:217], v[46:49]
	v_mfma_f32_16x16x32_bf16 v[42:45], v[146:149], v[198:201], v[42:45]
	v_mfma_f32_16x16x32_bf16 v[42:45], v[150:153], v[214:217], v[42:45]
	v_mfma_f32_16x16x32_bf16 v[30:33], v[134:137], v[218:221], v[30:33]
	v_mfma_f32_16x16x32_bf16 v[30:33], v[142:145], v[222:225], v[30:33]
	v_mfma_f32_16x16x32_bf16 v[26:29], v[146:149], v[218:221], v[26:29]
	v_mfma_f32_16x16x32_bf16 v[26:29], v[150:153], v[222:225], v[26:29]
	v_mfma_f32_16x16x32_bf16 v[14:17], v[134:137], v[226:229], v[14:17]
	v_mfma_f32_16x16x32_bf16 v[14:17], v[142:145], v[230:233], v[14:17]
	v_mfma_f32_16x16x32_bf16 v[10:13], v[146:149], v[226:229], v[10:13]
	v_mfma_f32_16x16x32_bf16 v[10:13], v[150:153], v[230:233], v[10:13]
	s_setprio 0
	s_setprio 1
	v_mfma_f32_16x16x32_bf16 v[54:57], v[154:157], v[190:193], v[54:57]
	v_mfma_f32_16x16x32_bf16 v[54:57], v[158:161], v[194:197], v[54:57]
	v_mfma_f32_16x16x32_bf16 v[50:53], v[182:185], v[190:193], v[50:53]
	v_mfma_f32_16x16x32_bf16 v[50:53], v[186:189], v[194:197], v[50:53]
	v_mfma_f32_16x16x32_bf16 v[38:41], v[154:157], v[198:201], v[38:41]
	v_mfma_f32_16x16x32_bf16 v[38:41], v[158:161], v[214:217], v[38:41]
	v_mfma_f32_16x16x32_bf16 v[34:37], v[182:185], v[198:201], v[34:37]
	v_mfma_f32_16x16x32_bf16 v[34:37], v[186:189], v[214:217], v[34:37]
	v_mfma_f32_16x16x32_bf16 v[22:25], v[154:157], v[218:221], v[22:25]
	v_mfma_f32_16x16x32_bf16 v[22:25], v[158:161], v[222:225], v[22:25]
	v_mfma_f32_16x16x32_bf16 v[18:21], v[182:185], v[218:221], v[18:21]
	v_mfma_f32_16x16x32_bf16 v[18:21], v[186:189], v[222:225], v[18:21]
	v_mfma_f32_16x16x32_bf16 v[6:9], v[154:157], v[226:229], v[6:9]
	v_mfma_f32_16x16x32_bf16 v[6:9], v[158:161], v[230:233], v[6:9]
	v_mfma_f32_16x16x32_bf16 v[2:5], v[182:185], v[226:229], v[2:5]
	v_mfma_f32_16x16x32_bf16 v[2:5], v[186:189], v[230:233], v[2:5]
	s_setprio 0
	s_barrier
	s_add_i32 s20, 0, 0x18000
	s_add_i32 s21, 0, 0x1c000
	v_add_u32_e32 v150, s20, v139
	v_add_u32_e32 v186, s21, v139
	ds_read_b128 v[134:137], v150
	ds_read_b128 v[142:145], v150 offset:1024
	ds_read_b128 v[146:149], v150 offset:2048
	ds_read_b128 v[150:153], v150 offset:3072
	ds_read_b128 v[154:157], v186
	ds_read_b128 v[158:161], v186 offset:1024
	ds_read_b128 v[182:185], v186 offset:2048
	ds_read_b128 v[186:189], v186 offset:3072
	s_mov_b32 m0, s91
	v_lshl_add_u64 v[234:235], v[202:203], 0, s[72:73]
	ds_read_b128 v[190:193], v141 offset:32768
	ds_read_b128 v[194:197], v141 offset:33792
	ds_read_b128 v[198:201], v141 offset:34816
	ds_read_b128 v[214:217], v141 offset:35840
	ds_read_b128 v[218:221], v141 offset:36864
	ds_read_b128 v[222:225], v141 offset:37888
	ds_read_b128 v[226:229], v141 offset:38912
	ds_read_b128 v[230:233], v141 offset:39936
	global_load_lds_dwordx4 v[234:235], off
	v_lshl_add_u64 v[234:235], v[202:203], 0, s[74:75]
	s_mov_b32 m0, s96
	s_nop 0
	global_load_lds_dwordx4 v[234:235], off
	s_waitcnt vmcnt(8)
	s_waitcnt lgkmcnt(0)
	s_barrier
	s_setprio 1
	s_waitcnt lgkmcnt(0)
	v_mfma_f32_16x16x32_bf16 v[126:129], v[134:137], v[190:193], v[126:129]
	v_mfma_f32_16x16x32_bf16 v[126:129], v[142:145], v[194:197], v[126:129]
	v_mfma_f32_16x16x32_bf16 v[122:125], v[146:149], v[190:193], v[122:125]
	v_mfma_f32_16x16x32_bf16 v[122:125], v[150:153], v[194:197], v[122:125]
	v_mfma_f32_16x16x32_bf16 v[110:113], v[134:137], v[198:201], v[110:113]
	v_mfma_f32_16x16x32_bf16 v[110:113], v[142:145], v[214:217], v[110:113]
	v_mfma_f32_16x16x32_bf16 v[106:109], v[146:149], v[198:201], v[106:109]
	v_mfma_f32_16x16x32_bf16 v[106:109], v[150:153], v[214:217], v[106:109]
	v_mfma_f32_16x16x32_bf16 v[94:97], v[134:137], v[218:221], v[94:97]
	v_mfma_f32_16x16x32_bf16 v[94:97], v[142:145], v[222:225], v[94:97]
	v_mfma_f32_16x16x32_bf16 v[90:93], v[146:149], v[218:221], v[90:93]
	v_mfma_f32_16x16x32_bf16 v[90:93], v[150:153], v[222:225], v[90:93]
	v_mfma_f32_16x16x32_bf16 v[78:81], v[134:137], v[226:229], v[78:81]
	v_mfma_f32_16x16x32_bf16 v[78:81], v[142:145], v[230:233], v[78:81]
	v_mfma_f32_16x16x32_bf16 v[74:77], v[146:149], v[226:229], v[74:77]
	v_mfma_f32_16x16x32_bf16 v[74:77], v[150:153], v[230:233], v[74:77]
	s_setprio 0
	s_setprio 1
	v_mfma_f32_16x16x32_bf16 v[118:121], v[154:157], v[190:193], v[118:121]
	v_mfma_f32_16x16x32_bf16 v[118:121], v[158:161], v[194:197], v[118:121]
	v_mfma_f32_16x16x32_bf16 v[114:117], v[182:185], v[190:193], v[114:117]
	v_mfma_f32_16x16x32_bf16 v[114:117], v[186:189], v[194:197], v[114:117]
	v_mfma_f32_16x16x32_bf16 v[102:105], v[154:157], v[198:201], v[102:105]
	v_mfma_f32_16x16x32_bf16 v[102:105], v[158:161], v[214:217], v[102:105]
	v_mfma_f32_16x16x32_bf16 v[98:101], v[182:185], v[198:201], v[98:101]
	v_mfma_f32_16x16x32_bf16 v[98:101], v[186:189], v[214:217], v[98:101]
	v_mfma_f32_16x16x32_bf16 v[86:89], v[154:157], v[218:221], v[86:89]
	v_mfma_f32_16x16x32_bf16 v[86:89], v[158:161], v[222:225], v[86:89]
	v_mfma_f32_16x16x32_bf16 v[82:85], v[182:185], v[218:221], v[82:85]
	v_mfma_f32_16x16x32_bf16 v[82:85], v[186:189], v[222:225], v[82:85]
	v_mfma_f32_16x16x32_bf16 v[70:73], v[154:157], v[226:229], v[70:73]
	v_mfma_f32_16x16x32_bf16 v[70:73], v[158:161], v[230:233], v[70:73]
	v_mfma_f32_16x16x32_bf16 v[66:69], v[182:185], v[226:229], v[66:69]
	v_mfma_f32_16x16x32_bf16 v[66:69], v[186:189], v[230:233], v[66:69]
	s_setprio 0
	s_barrier
	s_add_i32 s20, s20, s88
	v_lshl_add_u64 v[234:235], v[162:163], 0, s[34:35]
	s_mov_b32 m0, s20
	ds_read_b128 v[190:193], v141 offset:49152
	ds_read_b128 v[194:197], v141 offset:50176
	ds_read_b128 v[198:201], v141 offset:51200
	ds_read_b128 v[214:217], v141 offset:52224
	ds_read_b128 v[218:221], v141 offset:53248
	ds_read_b128 v[222:225], v141 offset:54272
	ds_read_b128 v[226:229], v141 offset:55296
	ds_read_b128 v[230:233], v141 offset:56320
	global_load_lds_dwordx4 v[234:235], off
	v_lshl_add_u64 v[234:235], v[162:163], 0, s[80:81]
	s_add_i32 m0, s20, 0x2000
	s_add_i32 s20, s21, s88
	global_load_lds_dwordx4 v[234:235], off
	v_lshl_add_u64 v[234:235], v[162:163], 0, s[38:39]
	s_mov_b32 m0, s20
	v_lshl_add_u64 v[162:163], v[162:163], 0, s[86:87]
	global_load_lds_dwordx4 v[234:235], off
	s_add_i32 m0, s20, 0x2000
	s_nop 0
	global_load_lds_dwordx4 v[162:163], off
	v_lshl_add_u64 v[162:163], v[202:203], 0, s[34:35]
	s_mov_b32 m0, s97
	s_nop 0
	global_load_lds_dwordx4 v[162:163], off
	v_lshl_add_u64 v[162:163], v[202:203], 0, s[80:81]
	s_mov_b32 m0, s58
	s_nop 0
	global_load_lds_dwordx4 v[162:163], off
	s_waitcnt vmcnt(8)
	s_waitcnt lgkmcnt(0)
	s_barrier
	s_setprio 1
	s_waitcnt lgkmcnt(0)
	v_mfma_f32_16x16x32_bf16 v[62:65], v[134:137], v[190:193], v[62:65]
	v_mfma_f32_16x16x32_bf16 v[62:65], v[142:145], v[194:197], v[62:65]
	v_mfma_f32_16x16x32_bf16 v[58:61], v[146:149], v[190:193], v[58:61]
	v_mfma_f32_16x16x32_bf16 v[58:61], v[150:153], v[194:197], v[58:61]
	v_mfma_f32_16x16x32_bf16 v[46:49], v[134:137], v[198:201], v[46:49]
	v_mfma_f32_16x16x32_bf16 v[46:49], v[142:145], v[214:217], v[46:49]
	v_mfma_f32_16x16x32_bf16 v[42:45], v[146:149], v[198:201], v[42:45]
	v_mfma_f32_16x16x32_bf16 v[42:45], v[150:153], v[214:217], v[42:45]
	v_mfma_f32_16x16x32_bf16 v[30:33], v[134:137], v[218:221], v[30:33]
	v_mfma_f32_16x16x32_bf16 v[30:33], v[142:145], v[222:225], v[30:33]
	v_mfma_f32_16x16x32_bf16 v[26:29], v[146:149], v[218:221], v[26:29]
	v_mfma_f32_16x16x32_bf16 v[26:29], v[150:153], v[222:225], v[26:29]
	v_mfma_f32_16x16x32_bf16 v[14:17], v[134:137], v[226:229], v[14:17]
	v_mfma_f32_16x16x32_bf16 v[14:17], v[142:145], v[230:233], v[14:17]
	v_mfma_f32_16x16x32_bf16 v[10:13], v[146:149], v[226:229], v[10:13]
	v_mfma_f32_16x16x32_bf16 v[10:13], v[150:153], v[230:233], v[10:13]
	s_setprio 0
	s_setprio 1
	v_mfma_f32_16x16x32_bf16 v[54:57], v[154:157], v[190:193], v[54:57]
	v_mfma_f32_16x16x32_bf16 v[54:57], v[158:161], v[194:197], v[54:57]
	v_mfma_f32_16x16x32_bf16 v[50:53], v[182:185], v[190:193], v[50:53]
	v_mfma_f32_16x16x32_bf16 v[50:53], v[186:189], v[194:197], v[50:53]
	v_mfma_f32_16x16x32_bf16 v[38:41], v[154:157], v[198:201], v[38:41]
	v_mfma_f32_16x16x32_bf16 v[38:41], v[158:161], v[214:217], v[38:41]
	v_mfma_f32_16x16x32_bf16 v[34:37], v[182:185], v[198:201], v[34:37]
	v_mfma_f32_16x16x32_bf16 v[34:37], v[186:189], v[214:217], v[34:37]
	v_mfma_f32_16x16x32_bf16 v[22:25], v[154:157], v[218:221], v[22:25]
	v_mfma_f32_16x16x32_bf16 v[22:25], v[158:161], v[222:225], v[22:25]
	v_mfma_f32_16x16x32_bf16 v[18:21], v[182:185], v[218:221], v[18:21]
	v_mfma_f32_16x16x32_bf16 v[18:21], v[186:189], v[222:225], v[18:21]
	v_mfma_f32_16x16x32_bf16 v[6:9], v[154:157], v[226:229], v[6:9]
	v_mfma_f32_16x16x32_bf16 v[6:9], v[158:161], v[230:233], v[6:9]
	v_mfma_f32_16x16x32_bf16 v[2:5], v[182:185], v[226:229], v[2:5]
	v_mfma_f32_16x16x32_bf16 v[2:5], v[186:189], v[230:233], v[2:5]
	s_setprio 0
	s_barrier
	s_add_i32 s84, s84, 2
	s_add_u32 s6, s6, 0x100
	s_addc_u32 s7, s7, 0
	s_add_u32 s49, s49, 0x100
	s_addc_u32 s51, s51, 0
	s_cmp_gt_u32 s84, 5
	s_cbranch_scc0 .LBB0_604
	s_and_b64 vcc, exec, s[52:53]
	s_cbranch_vccz .LBB0_607
	s_barrier

.LBB0_642:
	s_add_u32 s88, s60, s76
	s_addc_u32 s89, s61, s77
	s_add_u32 s22, s88, 0x100
	s_addc_u32 s23, s89, 0
	s_and_b64 s[20:21], s[68:69], exec
	s_cselect_b32 s78, s84, s22
	s_cselect_b32 s79, s51, s23
	s_add_u32 s20, s58, s76
	s_addc_u32 s21, s59, s77
	s_add_u32 s22, s20, 0x100
	s_addc_u32 s23, s21, 0
	s_add_i32 s40, 0, 0x10000
	s_and_b64 s[20:21], s[68:69], exec
	s_cselect_b32 s68, s85, s22
	s_cselect_b32 s69, s49, s23
	s_add_i32 s20, 0, 0x14000
	v_add_u32_e32 v148, s40, v133
	v_add_u32_e32 v182, s20, v133
	ds_read_b128 v[136:139], v148
	ds_read_b128 v[140:143], v148 offset:1024
	ds_read_b128 v[144:147], v148 offset:2048
	ds_read_b128 v[148:151], v148 offset:3072
	ds_read_b128 v[152:155], v182
	ds_read_b128 v[156:159], v182 offset:1024
	ds_read_b128 v[160:163], v182 offset:2048
	ds_read_b128 v[182:185], v182 offset:3072
	s_add_i32 s86, 0, 0x18000
	s_add_i32 s77, 0, 0x1c000
	s_add_i32 vcc_hi, s40, s46
	s_add_i32 vcc_lo, s20, s46
	s_add_i32 s76, s86, s46
	s_add_i32 s43, s77, s46
	s_add_i32 m0, s47, 0xc000
	s_add_i32 s21, s47, 0xe000
	s_add_i32 s42, vcc_hi, 0x2000
	s_add_i32 s87, vcc_lo, 0x2000
	s_add_i32 s41, s76, 0x2000
	s_add_i32 s40, s43, 0x2000
	v_lshl_add_u64 v[202:203], s[88:89], 0, v[130:131]
	v_lshl_add_u64 v[230:231], v[202:203], 0, s[80:81]
	ds_read_b128 v[186:189], v135
	ds_read_b128 v[190:193], v135 offset:1024
	ds_read_b128 v[194:197], v135 offset:2048
	ds_read_b128 v[198:201], v135 offset:3072
	ds_read_b128 v[214:217], v135 offset:4096
	ds_read_b128 v[218:221], v135 offset:5120
	ds_read_b128 v[222:225], v135 offset:6144
	ds_read_b128 v[226:229], v135 offset:7168
	global_load_lds_dwordx4 v[230:231], off
	v_lshl_add_u64 v[202:203], v[202:203], 0, s[30:31]
	s_mov_b32 m0, s21
	s_nop 0
	global_load_lds_dwordx4 v[202:203], off
	s_waitcnt vmcnt(8)
	s_waitcnt lgkmcnt(0)
	s_barrier
	s_setprio 1
	s_waitcnt lgkmcnt(0)
	v_mfma_f32_16x16x32_bf16 v[126:129], v[136:139], v[186:189], v[126:129]
	v_mfma_f32_16x16x32_bf16 v[126:129], v[140:143], v[190:193], v[126:129]
	v_mfma_f32_16x16x32_bf16 v[122:125], v[144:147], v[186:189], v[122:125]
	v_mfma_f32_16x16x32_bf16 v[122:125], v[148:151], v[190:193], v[122:125]
	v_mfma_f32_16x16x32_bf16 v[118:121], v[136:139], v[194:197], v[118:121]
	v_mfma_f32_16x16x32_bf16 v[118:121], v[140:143], v[198:201], v[118:121]
	v_mfma_f32_16x16x32_bf16 v[110:113], v[144:147], v[194:197], v[110:113]
	v_mfma_f32_16x16x32_bf16 v[110:113], v[148:151], v[198:201], v[110:113]
	v_mfma_f32_16x16x32_bf16 v[102:105], v[136:139], v[214:217], v[102:105]
	v_mfma_f32_16x16x32_bf16 v[102:105], v[140:143], v[218:221], v[102:105]
	v_mfma_f32_16x16x32_bf16 v[94:97], v[144:147], v[214:217], v[94:97]
	v_mfma_f32_16x16x32_bf16 v[94:97], v[148:151], v[218:221], v[94:97]
	v_mfma_f32_16x16x32_bf16 v[86:89], v[136:139], v[222:225], v[86:89]
	v_mfma_f32_16x16x32_bf16 v[86:89], v[140:143], v[226:229], v[86:89]
	v_mfma_f32_16x16x32_bf16 v[78:81], v[144:147], v[222:225], v[78:81]
	v_mfma_f32_16x16x32_bf16 v[78:81], v[148:151], v[226:229], v[78:81]
	s_setprio 0
	s_setprio 1
	v_mfma_f32_16x16x32_bf16 v[114:117], v[152:155], v[186:189], v[114:117]
	v_mfma_f32_16x16x32_bf16 v[114:117], v[156:159], v[190:193], v[114:117]
	v_mfma_f32_16x16x32_bf16 v[106:109], v[160:163], v[186:189], v[106:109]
	v_mfma_f32_16x16x32_bf16 v[106:109], v[182:185], v[190:193], v[106:109]
	v_mfma_f32_16x16x32_bf16 v[98:101], v[152:155], v[194:197], v[98:101]
	v_mfma_f32_16x16x32_bf16 v[98:101], v[156:159], v[198:201], v[98:101]
	v_mfma_f32_16x16x32_bf16 v[90:93], v[160:163], v[194:197], v[90:93]
	v_mfma_f32_16x16x32_bf16 v[90:93], v[182:185], v[198:201], v[90:93]
	v_mfma_f32_16x16x32_bf16 v[82:85], v[152:155], v[214:217], v[82:85]
	v_mfma_f32_16x16x32_bf16 v[82:85], v[156:159], v[218:221], v[82:85]
	v_mfma_f32_16x16x32_bf16 v[74:77], v[160:163], v[214:217], v[74:77]
	v_mfma_f32_16x16x32_bf16 v[74:77], v[182:185], v[218:221], v[74:77]
	v_mfma_f32_16x16x32_bf16 v[70:73], v[152:155], v[222:225], v[70:73]
	v_mfma_f32_16x16x32_bf16 v[70:73], v[156:159], v[226:229], v[70:73]
	v_mfma_f32_16x16x32_bf16 v[66:69], v[160:163], v[222:225], v[66:69]
	v_mfma_f32_16x16x32_bf16 v[66:69], v[182:185], v[226:229], v[66:69]
	s_setprio 0
	s_barrier
	s_mov_b32 m0, vcc_hi
	v_lshl_add_u64 v[202:203], s[68:69], 0, v[0:1]
	ds_read_b128 v[186:189], v135 offset:16384
	ds_read_b128 v[190:193], v135 offset:17408
	ds_read_b128 v[194:197], v135 offset:18432
	ds_read_b128 v[198:201], v135 offset:19456
	ds_read_b128 v[214:217], v135 offset:20480
	ds_read_b128 v[218:221], v135 offset:21504
	ds_read_b128 v[222:225], v135 offset:22528
	ds_read_b128 v[226:229], v135 offset:23552
	global_load_lds_dwordx4 v[202:203], off
	v_lshl_add_u64 v[230:231], v[202:203], 0, s[36:37]
	s_mov_b32 m0, s42
	s_nop 0
	global_load_lds_dwordx4 v[230:231], off
	v_lshl_add_u64 v[230:231], v[202:203], 0, s[64:65]
	s_mov_b32 m0, vcc_lo
	s_nop 0
	global_load_lds_dwordx4 v[230:231], off
	v_lshl_add_u64 v[230:231], v[202:203], 0, s[8:9]
	s_mov_b32 m0, s87
	s_nop 0
	global_load_lds_dwordx4 v[230:231], off
	v_lshl_add_u64 v[230:231], s[78:79], 0, v[130:131]
	s_mov_b32 m0, s47
	v_lshl_add_u64 v[232:233], v[230:231], 0, s[36:37]
	global_load_lds_dwordx4 v[230:231], off
	s_mov_b32 m0, s90
	s_nop 0
	global_load_lds_dwordx4 v[232:233], off
	s_waitcnt vmcnt(8)
	s_waitcnt lgkmcnt(0)
	s_barrier
	s_setprio 1
	s_waitcnt lgkmcnt(0)
	v_mfma_f32_16x16x32_bf16 v[62:65], v[136:139], v[186:189], v[62:65]
	v_mfma_f32_16x16x32_bf16 v[62:65], v[140:143], v[190:193], v[62:65]
	v_mfma_f32_16x16x32_bf16 v[58:61], v[144:147], v[186:189], v[58:61]
	v_mfma_f32_16x16x32_bf16 v[58:61], v[148:151], v[190:193], v[58:61]
	v_mfma_f32_16x16x32_bf16 v[54:57], v[136:139], v[194:197], v[54:57]
	v_mfma_f32_16x16x32_bf16 v[54:57], v[140:143], v[198:201], v[54:57]
	v_mfma_f32_16x16x32_bf16 v[46:49], v[144:147], v[194:197], v[46:49]
	v_mfma_f32_16x16x32_bf16 v[46:49], v[148:151], v[198:201], v[46:49]
	v_mfma_f32_16x16x32_bf16 v[38:41], v[136:139], v[214:217], v[38:41]
	v_mfma_f32_16x16x32_bf16 v[38:41], v[140:143], v[218:221], v[38:41]
	v_mfma_f32_16x16x32_bf16 v[30:33], v[144:147], v[214:217], v[30:33]
	v_mfma_f32_16x16x32_bf16 v[30:33], v[148:151], v[218:221], v[30:33]
	v_mfma_f32_16x16x32_bf16 v[22:25], v[136:139], v[222:225], v[22:25]
	v_mfma_f32_16x16x32_bf16 v[22:25], v[140:143], v[226:229], v[22:25]
	v_mfma_f32_16x16x32_bf16 v[14:17], v[144:147], v[222:225], v[14:17]
	v_mfma_f32_16x16x32_bf16 v[14:17], v[148:151], v[226:229], v[14:17]
	s_setprio 0
	s_setprio 1
	v_mfma_f32_16x16x32_bf16 v[50:53], v[152:155], v[186:189], v[50:53]
	v_mfma_f32_16x16x32_bf16 v[50:53], v[156:159], v[190:193], v[50:53]
	v_mfma_f32_16x16x32_bf16 v[42:45], v[160:163], v[186:189], v[42:45]
	v_mfma_f32_16x16x32_bf16 v[42:45], v[182:185], v[190:193], v[42:45]
	v_mfma_f32_16x16x32_bf16 v[34:37], v[152:155], v[194:197], v[34:37]
	v_mfma_f32_16x16x32_bf16 v[34:37], v[156:159], v[198:201], v[34:37]
	v_mfma_f32_16x16x32_bf16 v[26:29], v[160:163], v[194:197], v[26:29]
	v_mfma_f32_16x16x32_bf16 v[26:29], v[182:185], v[198:201], v[26:29]
	v_mfma_f32_16x16x32_bf16 v[18:21], v[152:155], v[214:217], v[18:21]
	v_mfma_f32_16x16x32_bf16 v[18:21], v[156:159], v[218:221], v[18:21]
	v_mfma_f32_16x16x32_bf16 v[10:13], v[160:163], v[214:217], v[10:13]
	v_mfma_f32_16x16x32_bf16 v[10:13], v[182:185], v[218:221], v[10:13]
	v_mfma_f32_16x16x32_bf16 v[6:9], v[152:155], v[222:225], v[6:9]
	v_mfma_f32_16x16x32_bf16 v[6:9], v[156:159], v[226:229], v[6:9]
	v_mfma_f32_16x16x32_bf16 v[2:5], v[160:163], v[222:225], v[2:5]
	v_mfma_f32_16x16x32_bf16 v[2:5], v[182:185], v[226:229], v[2:5]
	s_setprio 0
	s_barrier
	v_add_u32_e32 v148, s86, v133
	v_add_u32_e32 v182, s77, v133
	ds_read_b128 v[136:139], v148
	ds_read_b128 v[140:143], v148 offset:1024
	ds_read_b128 v[144:147], v148 offset:2048
	ds_read_b128 v[148:151], v148 offset:3072
	ds_read_b128 v[152:155], v182
	ds_read_b128 v[156:159], v182 offset:1024
	ds_read_b128 v[160:163], v182 offset:2048
	ds_read_b128 v[182:185], v182 offset:3072
	s_mov_b32 m0, s91
	v_lshl_add_u64 v[232:233], v[230:231], 0, s[64:65]
	ds_read_b128 v[186:189], v135 offset:32768
	ds_read_b128 v[190:193], v135 offset:33792
	ds_read_b128 v[194:197], v135 offset:34816
	ds_read_b128 v[198:201], v135 offset:35840
	ds_read_b128 v[214:217], v135 offset:36864
	ds_read_b128 v[218:221], v135 offset:37888
	ds_read_b128 v[222:225], v135 offset:38912
	ds_read_b128 v[226:229], v135 offset:39936
	global_load_lds_dwordx4 v[232:233], off
	v_lshl_add_u64 v[232:233], v[230:231], 0, s[8:9]
	s_mov_b32 m0, s96
	s_nop 0
	global_load_lds_dwordx4 v[232:233], off
	s_waitcnt vmcnt(8)
	s_waitcnt lgkmcnt(0)
	s_barrier
	s_setprio 1
	s_waitcnt lgkmcnt(0)
	v_mfma_f32_16x16x32_bf16 v[126:129], v[136:139], v[186:189], v[126:129]
	v_mfma_f32_16x16x32_bf16 v[126:129], v[140:143], v[190:193], v[126:129]
	v_mfma_f32_16x16x32_bf16 v[122:125], v[144:147], v[186:189], v[122:125]
	v_mfma_f32_16x16x32_bf16 v[122:125], v[148:151], v[190:193], v[122:125]
	v_mfma_f32_16x16x32_bf16 v[118:121], v[136:139], v[194:197], v[118:121]
	v_mfma_f32_16x16x32_bf16 v[118:121], v[140:143], v[198:201], v[118:121]
	v_mfma_f32_16x16x32_bf16 v[110:113], v[144:147], v[194:197], v[110:113]
	v_mfma_f32_16x16x32_bf16 v[110:113], v[148:151], v[198:201], v[110:113]
	v_mfma_f32_16x16x32_bf16 v[102:105], v[136:139], v[214:217], v[102:105]
	v_mfma_f32_16x16x32_bf16 v[102:105], v[140:143], v[218:221], v[102:105]
	v_mfma_f32_16x16x32_bf16 v[94:97], v[144:147], v[214:217], v[94:97]
	v_mfma_f32_16x16x32_bf16 v[94:97], v[148:151], v[218:221], v[94:97]
	v_mfma_f32_16x16x32_bf16 v[86:89], v[136:139], v[222:225], v[86:89]
	v_mfma_f32_16x16x32_bf16 v[86:89], v[140:143], v[226:229], v[86:89]
	v_mfma_f32_16x16x32_bf16 v[78:81], v[144:147], v[222:225], v[78:81]
	v_mfma_f32_16x16x32_bf16 v[78:81], v[148:151], v[226:229], v[78:81]
	s_setprio 0
	s_setprio 1
	v_mfma_f32_16x16x32_bf16 v[114:117], v[152:155], v[186:189], v[114:117]
	v_mfma_f32_16x16x32_bf16 v[114:117], v[156:159], v[190:193], v[114:117]
	v_mfma_f32_16x16x32_bf16 v[106:109], v[160:163], v[186:189], v[106:109]
	v_mfma_f32_16x16x32_bf16 v[106:109], v[182:185], v[190:193], v[106:109]
	v_mfma_f32_16x16x32_bf16 v[98:101], v[152:155], v[194:197], v[98:101]
	v_mfma_f32_16x16x32_bf16 v[98:101], v[156:159], v[198:201], v[98:101]
	v_mfma_f32_16x16x32_bf16 v[90:93], v[160:163], v[194:197], v[90:93]
	v_mfma_f32_16x16x32_bf16 v[90:93], v[182:185], v[198:201], v[90:93]
	v_mfma_f32_16x16x32_bf16 v[82:85], v[152:155], v[214:217], v[82:85]
	v_mfma_f32_16x16x32_bf16 v[82:85], v[156:159], v[218:221], v[82:85]
	v_mfma_f32_16x16x32_bf16 v[74:77], v[160:163], v[214:217], v[74:77]
	v_mfma_f32_16x16x32_bf16 v[74:77], v[182:185], v[218:221], v[74:77]
	v_mfma_f32_16x16x32_bf16 v[70:73], v[152:155], v[222:225], v[70:73]
	v_mfma_f32_16x16x32_bf16 v[70:73], v[156:159], v[226:229], v[70:73]
	v_mfma_f32_16x16x32_bf16 v[66:69], v[160:163], v[222:225], v[66:69]
	v_mfma_f32_16x16x32_bf16 v[66:69], v[182:185], v[226:229], v[66:69]
	s_setprio 0
	s_barrier
	s_mov_b32 m0, s76
	v_lshl_add_u64 v[232:233], v[202:203], 0, s[34:35]
	ds_read_b128 v[186:189], v135 offset:49152
	ds_read_b128 v[190:193], v135 offset:50176
	ds_read_b128 v[194:197], v135 offset:51200
	ds_read_b128 v[198:201], v135 offset:52224
	ds_read_b128 v[214:217], v135 offset:53248
	ds_read_b128 v[218:221], v135 offset:54272
	ds_read_b128 v[222:225], v135 offset:55296
	ds_read_b128 v[226:229], v135 offset:56320
	global_load_lds_dwordx4 v[232:233], off
	v_lshl_add_u64 v[232:233], v[202:203], 0, s[70:71]
	s_mov_b32 m0, s41
	s_nop 0
	global_load_lds_dwordx4 v[232:233], off
	v_lshl_add_u64 v[232:233], v[202:203], 0, s[80:81]
	s_mov_b32 m0, s43
	v_lshl_add_u64 v[202:203], v[202:203], 0, s[30:31]
	global_load_lds_dwordx4 v[232:233], off
	s_mov_b32 m0, s40
	s_nop 0
	global_load_lds_dwordx4 v[202:203], off
	v_lshl_add_u64 v[202:203], v[230:231], 0, s[34:35]
	s_mov_b32 m0, s97
	s_nop 0
	global_load_lds_dwordx4 v[202:203], off
	v_lshl_add_u64 v[202:203], v[230:231], 0, s[70:71]
	s_mov_b32 m0, s0
	s_nop 0
	global_load_lds_dwordx4 v[202:203], off
	s_waitcnt vmcnt(8)
	s_waitcnt lgkmcnt(0)
	s_barrier
	s_setprio 1
	s_waitcnt lgkmcnt(0)
	v_mfma_f32_16x16x32_bf16 v[62:65], v[136:139], v[186:189], v[62:65]
	v_mfma_f32_16x16x32_bf16 v[62:65], v[140:143], v[190:193], v[62:65]
	v_mfma_f32_16x16x32_bf16 v[58:61], v[144:147], v[186:189], v[58:61]
	v_mfma_f32_16x16x32_bf16 v[58:61], v[148:151], v[190:193], v[58:61]
	v_mfma_f32_16x16x32_bf16 v[54:57], v[136:139], v[194:197], v[54:57]
	v_mfma_f32_16x16x32_bf16 v[54:57], v[140:143], v[198:201], v[54:57]
	v_mfma_f32_16x16x32_bf16 v[46:49], v[144:147], v[194:197], v[46:49]
	v_mfma_f32_16x16x32_bf16 v[46:49], v[148:151], v[198:201], v[46:49]
	v_mfma_f32_16x16x32_bf16 v[38:41], v[136:139], v[214:217], v[38:41]
	v_mfma_f32_16x16x32_bf16 v[38:41], v[140:143], v[218:221], v[38:41]
	v_mfma_f32_16x16x32_bf16 v[30:33], v[144:147], v[214:217], v[30:33]
	v_mfma_f32_16x16x32_bf16 v[30:33], v[148:151], v[218:221], v[30:33]
	v_mfma_f32_16x16x32_bf16 v[22:25], v[136:139], v[222:225], v[22:25]
	v_mfma_f32_16x16x32_bf16 v[22:25], v[140:143], v[226:229], v[22:25]
	v_mfma_f32_16x16x32_bf16 v[14:17], v[144:147], v[222:225], v[14:17]
	v_mfma_f32_16x16x32_bf16 v[14:17], v[148:151], v[226:229], v[14:17]
	s_setprio 0
	s_setprio 1
	v_mfma_f32_16x16x32_bf16 v[50:53], v[152:155], v[186:189], v[50:53]
	v_mfma_f32_16x16x32_bf16 v[50:53], v[156:159], v[190:193], v[50:53]
	v_mfma_f32_16x16x32_bf16 v[42:45], v[160:163], v[186:189], v[42:45]
	v_mfma_f32_16x16x32_bf16 v[42:45], v[182:185], v[190:193], v[42:45]
	v_mfma_f32_16x16x32_bf16 v[34:37], v[152:155], v[194:197], v[34:37]
	v_mfma_f32_16x16x32_bf16 v[34:37], v[156:159], v[198:201], v[34:37]
	v_mfma_f32_16x16x32_bf16 v[26:29], v[160:163], v[194:197], v[26:29]
	v_mfma_f32_16x16x32_bf16 v[26:29], v[182:185], v[198:201], v[26:29]
	v_mfma_f32_16x16x32_bf16 v[18:21], v[152:155], v[214:217], v[18:21]
	v_mfma_f32_16x16x32_bf16 v[18:21], v[156:159], v[218:221], v[18:21]
	v_mfma_f32_16x16x32_bf16 v[10:13], v[160:163], v[214:217], v[10:13]
	v_mfma_f32_16x16x32_bf16 v[10:13], v[182:185], v[218:221], v[10:13]
	v_mfma_f32_16x16x32_bf16 v[6:9], v[152:155], v[222:225], v[6:9]
	v_mfma_f32_16x16x32_bf16 v[6:9], v[156:159], v[226:229], v[6:9]
	v_mfma_f32_16x16x32_bf16 v[2:5], v[160:163], v[222:225], v[2:5]
	v_mfma_f32_16x16x32_bf16 v[2:5], v[182:185], v[226:229], v[2:5]
	s_setprio 0
	s_barrier
	s_andn2_b64 vcc, exec, s[62:63]
	s_mov_b64 s[68:69], -1
	s_mov_b64 s[62:63], 0
	s_mov_b64 s[76:77], 0x100
	s_cbranch_vccz .LBB0_642
	v_readlane_b32 s12, v244, 8
	v_readlane_b32 s13, v244, 9
	s_and_b64 vcc, exec, s[12:13]
	v_readlane_b32 s85, v244, 4
	s_cbranch_vccz .LBB0_645
	s_barrier

.LBB0_778:
	s_add_u32 s20, s76, 0xfffc0080
	s_addc_u32 s21, s77, -1
	s_add_i32 s22, 0, 0x10000
	s_cmp_eq_u32 vcc_hi, 12
	s_cselect_b32 s79, s61, s21
	s_cselect_b32 s78, s85, s20
	s_cselect_b32 s21, s59, vcc_lo
	s_cselect_b32 s20, s86, s87
	s_add_i32 s23, 0, 0x14000
	v_add_u32_e32 v142, s22, v193
	v_add_u32_e32 v158, s23, v193
	ds_read_b128 v[130:133], v142
	ds_read_b128 v[134:137], v142 offset:1024
	ds_read_b128 v[138:141], v142 offset:2048
	ds_read_b128 v[142:145], v142 offset:3072
	ds_read_b128 v[146:149], v158
	ds_read_b128 v[150:153], v158 offset:1024
	ds_read_b128 v[154:157], v158 offset:2048
	ds_read_b128 v[158:161], v158 offset:3072
	v_lshl_add_u64 v[202:203], s[76:77], 0, v[182:183]
	s_add_i32 m0, s43, 0xc000
	ds_read_b128 v[184:187], v196
	ds_read_b128 v[188:191], v196 offset:1024
	ds_read_b128 v[198:201], v196 offset:2048
	ds_read_b128 v[214:217], v196 offset:3072
	ds_read_b128 v[218:221], v196 offset:4096
	ds_read_b128 v[222:225], v196 offset:5120
	ds_read_b128 v[226:229], v196 offset:6144
	ds_read_b128 v[230:233], v196 offset:7168
	global_load_lds_dwordx4 v[202:203], off
	v_lshl_add_u64 v[202:203], v[202:203], 0, s[72:73]
	s_add_i32 m0, s43, 0xe000
	s_nop 0
	global_load_lds_dwordx4 v[202:203], off
	s_waitcnt vmcnt(8)
	s_waitcnt lgkmcnt(0)
	s_barrier
	s_setprio 1
	s_waitcnt lgkmcnt(0)
	v_mfma_f32_16x16x32_bf16 v[126:129], v[130:133], v[184:187], v[126:129]
	v_mfma_f32_16x16x32_bf16 v[126:129], v[134:137], v[188:191], v[126:129]
	v_mfma_f32_16x16x32_bf16 v[122:125], v[138:141], v[184:187], v[122:125]
	v_mfma_f32_16x16x32_bf16 v[122:125], v[142:145], v[188:191], v[122:125]
	v_mfma_f32_16x16x32_bf16 v[110:113], v[130:133], v[198:201], v[110:113]
	v_mfma_f32_16x16x32_bf16 v[110:113], v[134:137], v[214:217], v[110:113]
	v_mfma_f32_16x16x32_bf16 v[106:109], v[138:141], v[198:201], v[106:109]
	v_mfma_f32_16x16x32_bf16 v[106:109], v[142:145], v[214:217], v[106:109]
	v_mfma_f32_16x16x32_bf16 v[94:97], v[130:133], v[218:221], v[94:97]
	v_mfma_f32_16x16x32_bf16 v[94:97], v[134:137], v[222:225], v[94:97]
	v_mfma_f32_16x16x32_bf16 v[90:93], v[138:141], v[218:221], v[90:93]
	v_mfma_f32_16x16x32_bf16 v[90:93], v[142:145], v[222:225], v[90:93]
	v_mfma_f32_16x16x32_bf16 v[78:81], v[130:133], v[226:229], v[78:81]
	v_mfma_f32_16x16x32_bf16 v[78:81], v[134:137], v[230:233], v[78:81]
	v_mfma_f32_16x16x32_bf16 v[74:77], v[138:141], v[226:229], v[74:77]
	v_mfma_f32_16x16x32_bf16 v[74:77], v[142:145], v[230:233], v[74:77]
	s_setprio 0
	s_setprio 1
	v_mfma_f32_16x16x32_bf16 v[118:121], v[146:149], v[184:187], v[118:121]
	v_mfma_f32_16x16x32_bf16 v[118:121], v[150:153], v[188:191], v[118:121]
	v_mfma_f32_16x16x32_bf16 v[114:117], v[154:157], v[184:187], v[114:117]
	v_mfma_f32_16x16x32_bf16 v[114:117], v[158:161], v[188:191], v[114:117]
	v_mfma_f32_16x16x32_bf16 v[102:105], v[146:149], v[198:201], v[102:105]
	v_mfma_f32_16x16x32_bf16 v[102:105], v[150:153], v[214:217], v[102:105]
	v_mfma_f32_16x16x32_bf16 v[98:101], v[154:157], v[198:201], v[98:101]
	v_mfma_f32_16x16x32_bf16 v[98:101], v[158:161], v[214:217], v[98:101]
	v_mfma_f32_16x16x32_bf16 v[86:89], v[146:149], v[218:221], v[86:89]
	v_mfma_f32_16x16x32_bf16 v[86:89], v[150:153], v[222:225], v[86:89]
	v_mfma_f32_16x16x32_bf16 v[82:85], v[154:157], v[218:221], v[82:85]
	v_mfma_f32_16x16x32_bf16 v[82:85], v[158:161], v[222:225], v[82:85]
	v_mfma_f32_16x16x32_bf16 v[70:73], v[146:149], v[226:229], v[70:73]
	v_mfma_f32_16x16x32_bf16 v[70:73], v[150:153], v[230:233], v[70:73]
	v_mfma_f32_16x16x32_bf16 v[66:69], v[154:157], v[226:229], v[66:69]
	v_mfma_f32_16x16x32_bf16 v[66:69], v[158:161], v[230:233], v[66:69]
	s_setprio 0
	s_barrier
	v_lshl_add_u64 v[202:203], s[20:21], 0, v[0:1]
	s_add_i32 s20, s22, s14
	s_mov_b32 m0, s20
	ds_read_b128 v[184:187], v196 offset:16384
	ds_read_b128 v[188:191], v196 offset:17408
	ds_read_b128 v[198:201], v196 offset:18432
	ds_read_b128 v[214:217], v196 offset:19456
	ds_read_b128 v[218:221], v196 offset:20480
	ds_read_b128 v[222:225], v196 offset:21504
	ds_read_b128 v[226:229], v196 offset:22528
	ds_read_b128 v[230:233], v196 offset:23552
	global_load_lds_dwordx4 v[202:203], off
	v_lshl_add_u64 v[234:235], v[202:203], 0, s[72:73]
	s_add_i32 m0, s20, 0x2000
	s_add_i32 s20, s23, s14
	global_load_lds_dwordx4 v[234:235], off
	v_lshl_add_u64 v[234:235], v[202:203], 0, s[28:29]
	s_mov_b32 m0, s20
	s_nop 0
	global_load_lds_dwordx4 v[234:235], off
	v_lshl_add_u64 v[234:235], v[202:203], 0, s[82:83]
	s_add_i32 m0, s20, 0x2000
	s_nop 0
	global_load_lds_dwordx4 v[234:235], off
	v_lshl_add_u64 v[234:235], s[78:79], 0, v[162:163]
	s_mov_b32 m0, s43
	v_lshl_add_u64 v[236:237], v[234:235], 0, s[72:73]
	global_load_lds_dwordx4 v[234:235], off
	s_mov_b32 m0, s46
	s_nop 0
	global_load_lds_dwordx4 v[236:237], off
	s_waitcnt vmcnt(8)
	s_waitcnt lgkmcnt(0)
	s_barrier
	s_setprio 1
	s_waitcnt lgkmcnt(0)
	v_mfma_f32_16x16x32_bf16 v[62:65], v[130:133], v[184:187], v[62:65]
	v_mfma_f32_16x16x32_bf16 v[62:65], v[134:137], v[188:191], v[62:65]
	v_mfma_f32_16x16x32_bf16 v[58:61], v[138:141], v[184:187], v[58:61]
	v_mfma_f32_16x16x32_bf16 v[58:61], v[142:145], v[188:191], v[58:61]
	v_mfma_f32_16x16x32_bf16 v[46:49], v[130:133], v[198:201], v[46:49]
	v_mfma_f32_16x16x32_bf16 v[46:49], v[134:137], v[214:217], v[46:49]
	v_mfma_f32_16x16x32_bf16 v[42:45], v[138:141], v[198:201], v[42:45]
	v_mfma_f32_16x16x32_bf16 v[42:45], v[142:145], v[214:217], v[42:45]
	v_mfma_f32_16x16x32_bf16 v[30:33], v[130:133], v[218:221], v[30:33]
	v_mfma_f32_16x16x32_bf16 v[30:33], v[134:137], v[222:225], v[30:33]
	v_mfma_f32_16x16x32_bf16 v[26:29], v[138:141], v[218:221], v[26:29]
	v_mfma_f32_16x16x32_bf16 v[26:29], v[142:145], v[222:225], v[26:29]
	v_mfma_f32_16x16x32_bf16 v[14:17], v[130:133], v[226:229], v[14:17]
	v_mfma_f32_16x16x32_bf16 v[14:17], v[134:137], v[230:233], v[14:17]
	v_mfma_f32_16x16x32_bf16 v[10:13], v[138:141], v[226:229], v[10:13]
	v_mfma_f32_16x16x32_bf16 v[10:13], v[142:145], v[230:233], v[10:13]
	s_setprio 0
	s_setprio 1
	v_mfma_f32_16x16x32_bf16 v[54:57], v[146:149], v[184:187], v[54:57]
	v_mfma_f32_16x16x32_bf16 v[54:57], v[150:153], v[188:191], v[54:57]
	v_mfma_f32_16x16x32_bf16 v[50:53], v[154:157], v[184:187], v[50:53]
	v_mfma_f32_16x16x32_bf16 v[50:53], v[158:161], v[188:191], v[50:53]
	v_mfma_f32_16x16x32_bf16 v[38:41], v[146:149], v[198:201], v[38:41]
	v_mfma_f32_16x16x32_bf16 v[38:41], v[150:153], v[214:217], v[38:41]
	v_mfma_f32_16x16x32_bf16 v[34:37], v[154:157], v[198:201], v[34:37]
	v_mfma_f32_16x16x32_bf16 v[34:37], v[158:161], v[214:217], v[34:37]
	v_mfma_f32_16x16x32_bf16 v[22:25], v[146:149], v[218:221], v[22:25]
	v_mfma_f32_16x16x32_bf16 v[22:25], v[150:153], v[222:225], v[22:25]
	v_mfma_f32_16x16x32_bf16 v[18:21], v[154:157], v[218:221], v[18:21]
	v_mfma_f32_16x16x32_bf16 v[18:21], v[158:161], v[222:225], v[18:21]
	v_mfma_f32_16x16x32_bf16 v[6:9], v[146:149], v[226:229], v[6:9]
	v_mfma_f32_16x16x32_bf16 v[6:9], v[150:153], v[230:233], v[6:9]
	v_mfma_f32_16x16x32_bf16 v[2:5], v[154:157], v[226:229], v[2:5]
	v_mfma_f32_16x16x32_bf16 v[2:5], v[158:161], v[230:233], v[2:5]
	s_setprio 0
	s_barrier
	s_add_i32 s20, 0, 0x18000
	s_add_i32 s21, 0, 0x1c000
	v_add_u32_e32 v142, s20, v193
	v_add_u32_e32 v158, s21, v193
	ds_read_b128 v[130:133], v142
	ds_read_b128 v[134:137], v142 offset:1024
	ds_read_b128 v[138:141], v142 offset:2048
	ds_read_b128 v[142:145], v142 offset:3072
	ds_read_b128 v[146:149], v158
	ds_read_b128 v[150:153], v158 offset:1024
	ds_read_b128 v[154:157], v158 offset:2048
	ds_read_b128 v[158:161], v158 offset:3072
	s_mov_b32 m0, s47
	v_lshl_add_u64 v[236:237], v[234:235], 0, s[28:29]
	ds_read_b128 v[184:187], v196 offset:32768
	ds_read_b128 v[188:191], v196 offset:33792
	ds_read_b128 v[198:201], v196 offset:34816
	ds_read_b128 v[214:217], v196 offset:35840
	ds_read_b128 v[218:221], v196 offset:36864
	ds_read_b128 v[222:225], v196 offset:37888
	ds_read_b128 v[226:229], v196 offset:38912
	ds_read_b128 v[230:233], v196 offset:39936
	global_load_lds_dwordx4 v[236:237], off
	v_lshl_add_u64 v[236:237], v[234:235], 0, s[82:83]
	s_mov_b32 m0, s88
	s_nop 0
	global_load_lds_dwordx4 v[236:237], off
	s_waitcnt vmcnt(8)
	s_waitcnt lgkmcnt(0)
	s_barrier
	s_setprio 1
	s_waitcnt lgkmcnt(0)
	v_mfma_f32_16x16x32_bf16 v[126:129], v[130:133], v[184:187], v[126:129]
	v_mfma_f32_16x16x32_bf16 v[126:129], v[134:137], v[188:191], v[126:129]
	v_mfma_f32_16x16x32_bf16 v[122:125], v[138:141], v[184:187], v[122:125]
	v_mfma_f32_16x16x32_bf16 v[122:125], v[142:145], v[188:191], v[122:125]
	v_mfma_f32_16x16x32_bf16 v[110:113], v[130:133], v[198:201], v[110:113]
	v_mfma_f32_16x16x32_bf16 v[110:113], v[134:137], v[214:217], v[110:113]
	v_mfma_f32_16x16x32_bf16 v[106:109], v[138:141], v[198:201], v[106:109]
	v_mfma_f32_16x16x32_bf16 v[106:109], v[142:145], v[214:217], v[106:109]
	v_mfma_f32_16x16x32_bf16 v[94:97], v[130:133], v[218:221], v[94:97]
	v_mfma_f32_16x16x32_bf16 v[94:97], v[134:137], v[222:225], v[94:97]
	v_mfma_f32_16x16x32_bf16 v[90:93], v[138:141], v[218:221], v[90:93]
	v_mfma_f32_16x16x32_bf16 v[90:93], v[142:145], v[222:225], v[90:93]
	v_mfma_f32_16x16x32_bf16 v[78:81], v[130:133], v[226:229], v[78:81]
	v_mfma_f32_16x16x32_bf16 v[78:81], v[134:137], v[230:233], v[78:81]
	v_mfma_f32_16x16x32_bf16 v[74:77], v[138:141], v[226:229], v[74:77]
	v_mfma_f32_16x16x32_bf16 v[74:77], v[142:145], v[230:233], v[74:77]
	s_setprio 0
	s_setprio 1
	v_mfma_f32_16x16x32_bf16 v[118:121], v[146:149], v[184:187], v[118:121]
	v_mfma_f32_16x16x32_bf16 v[118:121], v[150:153], v[188:191], v[118:121]
	v_mfma_f32_16x16x32_bf16 v[114:117], v[154:157], v[184:187], v[114:117]
	v_mfma_f32_16x16x32_bf16 v[114:117], v[158:161], v[188:191], v[114:117]
	v_mfma_f32_16x16x32_bf16 v[102:105], v[146:149], v[198:201], v[102:105]
	v_mfma_f32_16x16x32_bf16 v[102:105], v[150:153], v[214:217], v[102:105]
	v_mfma_f32_16x16x32_bf16 v[98:101], v[154:157], v[198:201], v[98:101]
	v_mfma_f32_16x16x32_bf16 v[98:101], v[158:161], v[214:217], v[98:101]
	v_mfma_f32_16x16x32_bf16 v[86:89], v[146:149], v[218:221], v[86:89]
	v_mfma_f32_16x16x32_bf16 v[86:89], v[150:153], v[222:225], v[86:89]
	v_mfma_f32_16x16x32_bf16 v[82:85], v[154:157], v[218:221], v[82:85]
	v_mfma_f32_16x16x32_bf16 v[82:85], v[158:161], v[222:225], v[82:85]
	v_mfma_f32_16x16x32_bf16 v[70:73], v[146:149], v[226:229], v[70:73]
	v_mfma_f32_16x16x32_bf16 v[70:73], v[150:153], v[230:233], v[70:73]
	v_mfma_f32_16x16x32_bf16 v[66:69], v[154:157], v[226:229], v[66:69]
	v_mfma_f32_16x16x32_bf16 v[66:69], v[158:161], v[230:233], v[66:69]
	s_setprio 0
	s_barrier
	s_add_i32 s20, s20, s14
	v_lshl_add_u64 v[236:237], v[202:203], 0, s[34:35]
	s_mov_b32 m0, s20
	ds_read_b128 v[184:187], v196 offset:49152
	ds_read_b128 v[188:191], v196 offset:50176
	ds_read_b128 v[198:201], v196 offset:51200
	ds_read_b128 v[214:217], v196 offset:52224
	ds_read_b128 v[218:221], v196 offset:53248
	ds_read_b128 v[222:225], v196 offset:54272
	ds_read_b128 v[226:229], v196 offset:55296
	ds_read_b128 v[230:233], v196 offset:56320
	global_load_lds_dwordx4 v[236:237], off
	v_lshl_add_u64 v[236:237], v[202:203], 0, s[38:39]
	s_add_i32 m0, s20, 0x2000
	s_add_i32 s20, s21, s14
	global_load_lds_dwordx4 v[236:237], off
	v_lshl_add_u64 v[236:237], v[202:203], 0, s[44:45]
	s_mov_b32 m0, s20
	v_lshl_add_u64 v[202:203], v[202:203], 0, s[10:11]
	global_load_lds_dwordx4 v[236:237], off
	s_add_i32 m0, s20, 0x2000
	s_nop 0
	global_load_lds_dwordx4 v[202:203], off
	v_lshl_add_u64 v[202:203], v[234:235], 0, s[34:35]
	s_mov_b32 m0, s89
	s_nop 0
	global_load_lds_dwordx4 v[202:203], off
	v_lshl_add_u64 v[202:203], v[234:235], 0, s[38:39]
	s_mov_b32 m0, s90
	s_nop 0
	global_load_lds_dwordx4 v[202:203], off
	s_waitcnt vmcnt(8)
	s_waitcnt lgkmcnt(0)
	s_barrier
	s_setprio 1
	s_waitcnt lgkmcnt(0)
	v_mfma_f32_16x16x32_bf16 v[62:65], v[130:133], v[184:187], v[62:65]
	v_mfma_f32_16x16x32_bf16 v[62:65], v[134:137], v[188:191], v[62:65]
	v_mfma_f32_16x16x32_bf16 v[58:61], v[138:141], v[184:187], v[58:61]
	v_mfma_f32_16x16x32_bf16 v[58:61], v[142:145], v[188:191], v[58:61]
	v_mfma_f32_16x16x32_bf16 v[46:49], v[130:133], v[198:201], v[46:49]
	v_mfma_f32_16x16x32_bf16 v[46:49], v[134:137], v[214:217], v[46:49]
	v_mfma_f32_16x16x32_bf16 v[42:45], v[138:141], v[198:201], v[42:45]
	v_mfma_f32_16x16x32_bf16 v[42:45], v[142:145], v[214:217], v[42:45]
	v_mfma_f32_16x16x32_bf16 v[30:33], v[130:133], v[218:221], v[30:33]
	v_mfma_f32_16x16x32_bf16 v[30:33], v[134:137], v[222:225], v[30:33]
	v_mfma_f32_16x16x32_bf16 v[26:29], v[138:141], v[218:221], v[26:29]
	v_mfma_f32_16x16x32_bf16 v[26:29], v[142:145], v[222:225], v[26:29]
	v_mfma_f32_16x16x32_bf16 v[14:17], v[130:133], v[226:229], v[14:17]
	v_mfma_f32_16x16x32_bf16 v[14:17], v[134:137], v[230:233], v[14:17]
	v_mfma_f32_16x16x32_bf16 v[10:13], v[138:141], v[226:229], v[10:13]
	v_mfma_f32_16x16x32_bf16 v[10:13], v[142:145], v[230:233], v[10:13]
	s_setprio 0
	s_setprio 1
	v_mfma_f32_16x16x32_bf16 v[54:57], v[146:149], v[184:187], v[54:57]
	v_mfma_f32_16x16x32_bf16 v[54:57], v[150:153], v[188:191], v[54:57]
	v_mfma_f32_16x16x32_bf16 v[50:53], v[154:157], v[184:187], v[50:53]
	v_mfma_f32_16x16x32_bf16 v[50:53], v[158:161], v[188:191], v[50:53]
	v_mfma_f32_16x16x32_bf16 v[38:41], v[146:149], v[198:201], v[38:41]
	v_mfma_f32_16x16x32_bf16 v[38:41], v[150:153], v[214:217], v[38:41]
	v_mfma_f32_16x16x32_bf16 v[34:37], v[154:157], v[198:201], v[34:37]
	v_mfma_f32_16x16x32_bf16 v[34:37], v[158:161], v[214:217], v[34:37]
	v_mfma_f32_16x16x32_bf16 v[22:25], v[146:149], v[218:221], v[22:25]
	v_mfma_f32_16x16x32_bf16 v[22:25], v[150:153], v[222:225], v[22:25]
	v_mfma_f32_16x16x32_bf16 v[18:21], v[154:157], v[218:221], v[18:21]
	v_mfma_f32_16x16x32_bf16 v[18:21], v[158:161], v[222:225], v[18:21]
	v_mfma_f32_16x16x32_bf16 v[6:9], v[146:149], v[226:229], v[6:9]
	v_mfma_f32_16x16x32_bf16 v[6:9], v[150:153], v[230:233], v[6:9]
	v_mfma_f32_16x16x32_bf16 v[2:5], v[154:157], v[226:229], v[2:5]
	v_mfma_f32_16x16x32_bf16 v[2:5], v[158:161], v[230:233], v[2:5]
	s_setprio 0
	s_barrier
	s_add_i32 vcc_hi, vcc_hi, 2
	s_add_u32 s76, s76, 0x100
	s_addc_u32 s77, s77, 0
	s_add_u32 s87, s87, 0x100
	s_addc_u32 vcc_lo, vcc_lo, 0
	s_cmp_gt_u32 vcc_hi, 13
	s_cbranch_scc0 .LBB0_778
	s_and_b64 vcc, exec, s[50:51]
	s_cbranch_vccz .LBB0_781
	s_barrier

.LBB0_850:
	s_add_u32 s20, s56, 0xfffc0080
	s_addc_u32 s21, s57, -1
	s_add_i32 vcc_lo, 0, 0x10000
	s_cmp_eq_u32 s91, 12
	s_cselect_b32 s59, s76, s21
	s_cselect_b32 s58, s77, s20
	v_add_u32_e32 v0, vcc_lo, v145
	s_cselect_b32 s21, s69, s87
	s_cselect_b32 s20, s79, s86
	s_add_i32 vcc_hi, 0, 0x14000
	ds_read_b128 v[138:141], v0
	ds_read_b128 v[146:149], v0 offset:1024
	ds_read_b128 v[150:153], v0 offset:2048
	ds_read_b128 v[158:161], v0 offset:3072
	v_add_u32_e32 v0, vcc_hi, v145
	ds_read_b128 v[182:185], v0
	ds_read_b128 v[186:189], v0 offset:1024
	ds_read_b128 v[190:193], v0 offset:2048
	ds_read_b128 v[194:197], v0 offset:3072
	v_lshl_add_u64 v[142:143], s[56:57], 0, v[136:137]
	s_add_i32 m0, s15, 0xc000
	ds_read_b128 v[198:201], v157
	ds_read_b128 v[214:217], v157 offset:1024
	ds_read_b128 v[218:221], v157 offset:2048
	ds_read_b128 v[222:225], v157 offset:3072
	ds_read_b128 v[226:229], v157 offset:4096
	ds_read_b128 v[230:233], v157 offset:5120
	ds_read_b128 v[234:237], v157 offset:6144
	ds_read_b128 v[238:241], v157 offset:7168
	global_load_lds_dwordx4 v[142:143], off
	v_lshl_add_u64 v[142:143], v[142:143], 0, s[72:73]
	s_add_i32 m0, s15, 0xe000
	s_nop 0
	global_load_lds_dwordx4 v[142:143], off
	s_waitcnt vmcnt(8)
	s_waitcnt lgkmcnt(0)
	s_barrier
	s_setprio 1
	s_waitcnt lgkmcnt(0)
	v_mfma_f32_16x16x32_bf16 v[126:129], v[138:141], v[198:201], v[126:129]
	v_mfma_f32_16x16x32_bf16 v[126:129], v[146:149], v[214:217], v[126:129]
	v_mfma_f32_16x16x32_bf16 v[122:125], v[150:153], v[198:201], v[122:125]
	v_mfma_f32_16x16x32_bf16 v[122:125], v[158:161], v[214:217], v[122:125]
	v_mfma_f32_16x16x32_bf16 v[110:113], v[138:141], v[218:221], v[110:113]
	v_mfma_f32_16x16x32_bf16 v[110:113], v[146:149], v[222:225], v[110:113]
	v_mfma_f32_16x16x32_bf16 v[106:109], v[150:153], v[218:221], v[106:109]
	v_mfma_f32_16x16x32_bf16 v[106:109], v[158:161], v[222:225], v[106:109]
	v_mfma_f32_16x16x32_bf16 v[94:97], v[138:141], v[226:229], v[94:97]
	v_mfma_f32_16x16x32_bf16 v[94:97], v[146:149], v[230:233], v[94:97]
	v_mfma_f32_16x16x32_bf16 v[90:93], v[150:153], v[226:229], v[90:93]
	v_mfma_f32_16x16x32_bf16 v[90:93], v[158:161], v[230:233], v[90:93]
	v_mfma_f32_16x16x32_bf16 v[78:81], v[138:141], v[234:237], v[78:81]
	v_mfma_f32_16x16x32_bf16 v[78:81], v[146:149], v[238:241], v[78:81]
	v_mfma_f32_16x16x32_bf16 v[74:77], v[150:153], v[234:237], v[74:77]
	v_mfma_f32_16x16x32_bf16 v[74:77], v[158:161], v[238:241], v[74:77]
	s_setprio 0
	s_setprio 1
	v_mfma_f32_16x16x32_bf16 v[118:121], v[182:185], v[198:201], v[118:121]
	v_mfma_f32_16x16x32_bf16 v[118:121], v[186:189], v[214:217], v[118:121]
	v_mfma_f32_16x16x32_bf16 v[114:117], v[190:193], v[198:201], v[114:117]
	v_mfma_f32_16x16x32_bf16 v[114:117], v[194:197], v[214:217], v[114:117]
	v_mfma_f32_16x16x32_bf16 v[102:105], v[182:185], v[218:221], v[102:105]
	v_mfma_f32_16x16x32_bf16 v[102:105], v[186:189], v[222:225], v[102:105]
	v_mfma_f32_16x16x32_bf16 v[98:101], v[190:193], v[218:221], v[98:101]
	v_mfma_f32_16x16x32_bf16 v[98:101], v[194:197], v[222:225], v[98:101]
	v_mfma_f32_16x16x32_bf16 v[86:89], v[182:185], v[226:229], v[86:89]
	v_mfma_f32_16x16x32_bf16 v[86:89], v[186:189], v[230:233], v[86:89]
	v_mfma_f32_16x16x32_bf16 v[82:85], v[190:193], v[226:229], v[82:85]
	v_mfma_f32_16x16x32_bf16 v[82:85], v[194:197], v[230:233], v[82:85]
	v_mfma_f32_16x16x32_bf16 v[70:73], v[182:185], v[234:237], v[70:73]
	v_mfma_f32_16x16x32_bf16 v[70:73], v[186:189], v[238:241], v[70:73]
	v_mfma_f32_16x16x32_bf16 v[66:69], v[190:193], v[234:237], v[66:69]
	v_mfma_f32_16x16x32_bf16 v[66:69], v[194:197], v[238:241], v[66:69]
	s_setprio 0
	s_barrier
	v_lshl_add_u64 v[142:143], s[20:21], 0, v[130:131]
	s_add_i32 s20, vcc_lo, s14
	s_mov_b32 m0, s20
	ds_read_b128 v[198:201], v157 offset:16384
	ds_read_b128 v[214:217], v157 offset:17408
	ds_read_b128 v[218:221], v157 offset:18432
	ds_read_b128 v[222:225], v157 offset:19456
	ds_read_b128 v[226:229], v157 offset:20480
	ds_read_b128 v[230:233], v157 offset:21504
	ds_read_b128 v[234:237], v157 offset:22528
	ds_read_b128 v[238:241], v157 offset:23552
	global_load_lds_dwordx4 v[142:143], off
	v_lshl_add_u64 v[162:163], v[142:143], 0, s[72:73]
	s_add_i32 m0, s20, 0x2000
	s_add_i32 s20, vcc_hi, s14
	global_load_lds_dwordx4 v[162:163], off
	v_lshl_add_u64 v[162:163], v[142:143], 0, s[28:29]
	s_mov_b32 m0, s20
	s_nop 0
	global_load_lds_dwordx4 v[162:163], off
	v_lshl_add_u64 v[162:163], v[142:143], 0, s[82:83]
	s_add_i32 m0, s20, 0x2000
	s_nop 0
	global_load_lds_dwordx4 v[162:163], off
	v_lshl_add_u64 v[162:163], s[58:59], 0, v[132:133]
	s_mov_b32 m0, s15
	v_lshl_add_u64 v[202:203], v[162:163], 0, s[72:73]
	global_load_lds_dwordx4 v[162:163], off
	s_mov_b32 m0, s42
	s_nop 0
	global_load_lds_dwordx4 v[202:203], off
	s_waitcnt vmcnt(8)
	s_waitcnt lgkmcnt(0)
	s_barrier
	s_setprio 1
	s_waitcnt lgkmcnt(0)
	v_mfma_f32_16x16x32_bf16 v[62:65], v[138:141], v[198:201], v[62:65]
	v_mfma_f32_16x16x32_bf16 v[62:65], v[146:149], v[214:217], v[62:65]
	v_mfma_f32_16x16x32_bf16 v[58:61], v[150:153], v[198:201], v[58:61]
	v_mfma_f32_16x16x32_bf16 v[58:61], v[158:161], v[214:217], v[58:61]
	v_mfma_f32_16x16x32_bf16 v[46:49], v[138:141], v[218:221], v[46:49]
	v_mfma_f32_16x16x32_bf16 v[46:49], v[146:149], v[222:225], v[46:49]
	v_mfma_f32_16x16x32_bf16 v[42:45], v[150:153], v[218:221], v[42:45]
	v_mfma_f32_16x16x32_bf16 v[42:45], v[158:161], v[222:225], v[42:45]
	v_mfma_f32_16x16x32_bf16 v[30:33], v[138:141], v[226:229], v[30:33]
	v_mfma_f32_16x16x32_bf16 v[30:33], v[146:149], v[230:233], v[30:33]
	v_mfma_f32_16x16x32_bf16 v[26:29], v[150:153], v[226:229], v[26:29]
	v_mfma_f32_16x16x32_bf16 v[26:29], v[158:161], v[230:233], v[26:29]
	v_mfma_f32_16x16x32_bf16 v[14:17], v[138:141], v[234:237], v[14:17]
	v_mfma_f32_16x16x32_bf16 v[14:17], v[146:149], v[238:241], v[14:17]
	v_mfma_f32_16x16x32_bf16 v[10:13], v[150:153], v[234:237], v[10:13]
	v_mfma_f32_16x16x32_bf16 v[10:13], v[158:161], v[238:241], v[10:13]
	s_setprio 0
	s_setprio 1
	v_mfma_f32_16x16x32_bf16 v[54:57], v[182:185], v[198:201], v[54:57]
	v_mfma_f32_16x16x32_bf16 v[54:57], v[186:189], v[214:217], v[54:57]
	v_mfma_f32_16x16x32_bf16 v[50:53], v[190:193], v[198:201], v[50:53]
	v_mfma_f32_16x16x32_bf16 v[50:53], v[194:197], v[214:217], v[50:53]
	v_mfma_f32_16x16x32_bf16 v[38:41], v[182:185], v[218:221], v[38:41]
	v_mfma_f32_16x16x32_bf16 v[38:41], v[186:189], v[222:225], v[38:41]
	v_mfma_f32_16x16x32_bf16 v[34:37], v[190:193], v[218:221], v[34:37]
	v_mfma_f32_16x16x32_bf16 v[34:37], v[194:197], v[222:225], v[34:37]
	v_mfma_f32_16x16x32_bf16 v[22:25], v[182:185], v[226:229], v[22:25]
	v_mfma_f32_16x16x32_bf16 v[22:25], v[186:189], v[230:233], v[22:25]
	v_mfma_f32_16x16x32_bf16 v[18:21], v[190:193], v[226:229], v[18:21]
	v_mfma_f32_16x16x32_bf16 v[18:21], v[194:197], v[230:233], v[18:21]
	v_mfma_f32_16x16x32_bf16 v[6:9], v[182:185], v[234:237], v[6:9]
	v_mfma_f32_16x16x32_bf16 v[6:9], v[186:189], v[238:241], v[6:9]
	v_mfma_f32_16x16x32_bf16 v[2:5], v[190:193], v[234:237], v[2:5]
	v_mfma_f32_16x16x32_bf16 v[2:5], v[194:197], v[238:241], v[2:5]
	s_setprio 0
	s_barrier
	s_add_i32 s20, 0, 0x18000
	v_add_u32_e32 v0, s20, v145
	s_add_i32 s21, 0, 0x1c000
	ds_read_b128 v[138:141], v0
	ds_read_b128 v[146:149], v0 offset:1024
	ds_read_b128 v[150:153], v0 offset:2048
	ds_read_b128 v[158:161], v0 offset:3072
	v_add_u32_e32 v0, s21, v145
	ds_read_b128 v[182:185], v0
	ds_read_b128 v[186:189], v0 offset:1024
	ds_read_b128 v[190:193], v0 offset:2048
	ds_read_b128 v[194:197], v0 offset:3072
	s_mov_b32 m0, s43
	v_lshl_add_u64 v[202:203], v[162:163], 0, s[28:29]
	ds_read_b128 v[198:201], v157 offset:32768
	ds_read_b128 v[214:217], v157 offset:33792
	ds_read_b128 v[218:221], v157 offset:34816
	ds_read_b128 v[222:225], v157 offset:35840
	ds_read_b128 v[226:229], v157 offset:36864
	ds_read_b128 v[230:233], v157 offset:37888
	ds_read_b128 v[234:237], v157 offset:38912
	ds_read_b128 v[238:241], v157 offset:39936
	global_load_lds_dwordx4 v[202:203], off
	v_lshl_add_u64 v[202:203], v[162:163], 0, s[82:83]
	s_mov_b32 m0, s46
	s_nop 0
	global_load_lds_dwordx4 v[202:203], off
	s_waitcnt vmcnt(8)
	s_waitcnt lgkmcnt(0)
	s_barrier
	s_setprio 1
	s_waitcnt lgkmcnt(0)
	v_mfma_f32_16x16x32_bf16 v[126:129], v[138:141], v[198:201], v[126:129]
	v_mfma_f32_16x16x32_bf16 v[126:129], v[146:149], v[214:217], v[126:129]
	v_mfma_f32_16x16x32_bf16 v[122:125], v[150:153], v[198:201], v[122:125]
	v_mfma_f32_16x16x32_bf16 v[122:125], v[158:161], v[214:217], v[122:125]
	v_mfma_f32_16x16x32_bf16 v[110:113], v[138:141], v[218:221], v[110:113]
	v_mfma_f32_16x16x32_bf16 v[110:113], v[146:149], v[222:225], v[110:113]
	v_mfma_f32_16x16x32_bf16 v[106:109], v[150:153], v[218:221], v[106:109]
	v_mfma_f32_16x16x32_bf16 v[106:109], v[158:161], v[222:225], v[106:109]
	v_mfma_f32_16x16x32_bf16 v[94:97], v[138:141], v[226:229], v[94:97]
	v_mfma_f32_16x16x32_bf16 v[94:97], v[146:149], v[230:233], v[94:97]
	v_mfma_f32_16x16x32_bf16 v[90:93], v[150:153], v[226:229], v[90:93]
	v_mfma_f32_16x16x32_bf16 v[90:93], v[158:161], v[230:233], v[90:93]
	v_mfma_f32_16x16x32_bf16 v[78:81], v[138:141], v[234:237], v[78:81]
	v_mfma_f32_16x16x32_bf16 v[78:81], v[146:149], v[238:241], v[78:81]
	v_mfma_f32_16x16x32_bf16 v[74:77], v[150:153], v[234:237], v[74:77]
	v_mfma_f32_16x16x32_bf16 v[74:77], v[158:161], v[238:241], v[74:77]
	s_setprio 0
	s_setprio 1
	v_mfma_f32_16x16x32_bf16 v[118:121], v[182:185], v[198:201], v[118:121]
	v_mfma_f32_16x16x32_bf16 v[118:121], v[186:189], v[214:217], v[118:121]
	v_mfma_f32_16x16x32_bf16 v[114:117], v[190:193], v[198:201], v[114:117]
	v_mfma_f32_16x16x32_bf16 v[114:117], v[194:197], v[214:217], v[114:117]
	v_mfma_f32_16x16x32_bf16 v[102:105], v[182:185], v[218:221], v[102:105]
	v_mfma_f32_16x16x32_bf16 v[102:105], v[186:189], v[222:225], v[102:105]
	v_mfma_f32_16x16x32_bf16 v[98:101], v[190:193], v[218:221], v[98:101]
	v_mfma_f32_16x16x32_bf16 v[98:101], v[194:197], v[222:225], v[98:101]
	v_mfma_f32_16x16x32_bf16 v[86:89], v[182:185], v[226:229], v[86:89]
	v_mfma_f32_16x16x32_bf16 v[86:89], v[186:189], v[230:233], v[86:89]
	v_mfma_f32_16x16x32_bf16 v[82:85], v[190:193], v[226:229], v[82:85]
	v_mfma_f32_16x16x32_bf16 v[82:85], v[194:197], v[230:233], v[82:85]
	v_mfma_f32_16x16x32_bf16 v[70:73], v[182:185], v[234:237], v[70:73]
	v_mfma_f32_16x16x32_bf16 v[70:73], v[186:189], v[238:241], v[70:73]
	v_mfma_f32_16x16x32_bf16 v[66:69], v[190:193], v[234:237], v[66:69]
	v_mfma_f32_16x16x32_bf16 v[66:69], v[194:197], v[238:241], v[66:69]
	s_setprio 0
	s_barrier
	s_add_i32 s20, s20, s14
	v_lshl_add_u64 v[202:203], v[142:143], 0, s[34:35]
	s_mov_b32 m0, s20
	ds_read_b128 v[198:201], v157 offset:49152
	ds_read_b128 v[214:217], v157 offset:50176
	ds_read_b128 v[218:221], v157 offset:51200
	ds_read_b128 v[222:225], v157 offset:52224
	ds_read_b128 v[226:229], v157 offset:53248
	ds_read_b128 v[230:233], v157 offset:54272
	ds_read_b128 v[234:237], v157 offset:55296
	ds_read_b128 v[238:241], v157 offset:56320
	global_load_lds_dwordx4 v[202:203], off
	v_lshl_add_u64 v[202:203], v[142:143], 0, s[38:39]
	s_add_i32 m0, s20, 0x2000
	s_add_i32 s20, s21, s14
	global_load_lds_dwordx4 v[202:203], off
	v_lshl_add_u64 v[202:203], v[142:143], 0, s[44:45]
	s_mov_b32 m0, s20
	v_lshl_add_u64 v[142:143], v[142:143], 0, s[10:11]
	global_load_lds_dwordx4 v[202:203], off
	s_add_i32 m0, s20, 0x2000
	s_nop 0
	global_load_lds_dwordx4 v[142:143], off
	v_lshl_add_u64 v[142:143], v[162:163], 0, s[34:35]
	s_mov_b32 m0, s47
	s_nop 0
	global_load_lds_dwordx4 v[142:143], off
	v_lshl_add_u64 v[142:143], v[162:163], 0, s[38:39]
	s_mov_b32 m0, s96
	s_nop 0
	global_load_lds_dwordx4 v[142:143], off
	s_waitcnt vmcnt(8)
	s_waitcnt lgkmcnt(0)
	s_barrier
	s_setprio 1
	s_waitcnt lgkmcnt(0)
	v_mfma_f32_16x16x32_bf16 v[62:65], v[138:141], v[198:201], v[62:65]
	v_mfma_f32_16x16x32_bf16 v[62:65], v[146:149], v[214:217], v[62:65]
	v_mfma_f32_16x16x32_bf16 v[58:61], v[150:153], v[198:201], v[58:61]
	v_mfma_f32_16x16x32_bf16 v[58:61], v[158:161], v[214:217], v[58:61]
	v_mfma_f32_16x16x32_bf16 v[46:49], v[138:141], v[218:221], v[46:49]
	v_mfma_f32_16x16x32_bf16 v[46:49], v[146:149], v[222:225], v[46:49]
	v_mfma_f32_16x16x32_bf16 v[42:45], v[150:153], v[218:221], v[42:45]
	v_mfma_f32_16x16x32_bf16 v[42:45], v[158:161], v[222:225], v[42:45]
	v_mfma_f32_16x16x32_bf16 v[30:33], v[138:141], v[226:229], v[30:33]
	v_mfma_f32_16x16x32_bf16 v[30:33], v[146:149], v[230:233], v[30:33]
	v_mfma_f32_16x16x32_bf16 v[26:29], v[150:153], v[226:229], v[26:29]
	v_mfma_f32_16x16x32_bf16 v[26:29], v[158:161], v[230:233], v[26:29]
	v_mfma_f32_16x16x32_bf16 v[14:17], v[138:141], v[234:237], v[14:17]
	v_mfma_f32_16x16x32_bf16 v[14:17], v[146:149], v[238:241], v[14:17]
	v_mfma_f32_16x16x32_bf16 v[10:13], v[150:153], v[234:237], v[10:13]
	v_mfma_f32_16x16x32_bf16 v[10:13], v[158:161], v[238:241], v[10:13]
	s_setprio 0
	s_setprio 1
	v_mfma_f32_16x16x32_bf16 v[54:57], v[182:185], v[198:201], v[54:57]
	v_mfma_f32_16x16x32_bf16 v[54:57], v[186:189], v[214:217], v[54:57]
	v_mfma_f32_16x16x32_bf16 v[50:53], v[190:193], v[198:201], v[50:53]
	v_mfma_f32_16x16x32_bf16 v[50:53], v[194:197], v[214:217], v[50:53]
	v_mfma_f32_16x16x32_bf16 v[38:41], v[182:185], v[218:221], v[38:41]
	v_mfma_f32_16x16x32_bf16 v[38:41], v[186:189], v[222:225], v[38:41]
	v_mfma_f32_16x16x32_bf16 v[34:37], v[190:193], v[218:221], v[34:37]
	v_mfma_f32_16x16x32_bf16 v[34:37], v[194:197], v[222:225], v[34:37]
	v_mfma_f32_16x16x32_bf16 v[22:25], v[182:185], v[226:229], v[22:25]
	v_mfma_f32_16x16x32_bf16 v[22:25], v[186:189], v[230:233], v[22:25]
	v_mfma_f32_16x16x32_bf16 v[18:21], v[190:193], v[226:229], v[18:21]
	v_mfma_f32_16x16x32_bf16 v[18:21], v[194:197], v[230:233], v[18:21]
	v_mfma_f32_16x16x32_bf16 v[6:9], v[182:185], v[234:237], v[6:9]
	v_mfma_f32_16x16x32_bf16 v[6:9], v[186:189], v[238:241], v[6:9]
	v_mfma_f32_16x16x32_bf16 v[2:5], v[190:193], v[234:237], v[2:5]
	v_mfma_f32_16x16x32_bf16 v[2:5], v[194:197], v[238:241], v[2:5]
	s_setprio 0
	s_barrier
	s_add_i32 s91, s91, 2
	s_add_u32 s56, s56, 0x100
	s_addc_u32 s57, s57, 0
	s_add_u32 s86, s86, 0x100
	s_addc_u32 s87, s87, 0
	s_cmp_gt_u32 s91, 13
	s_cbranch_scc0 .LBB0_850
	s_and_b64 vcc, exec, s[62:63]
	s_cbranch_vccz .LBB0_853
	s_barrier

.LBB0_1052:
	s_add_u32 s78, s58, s68
	s_addc_u32 s79, s59, s69
	s_add_u32 s76, s78, 0x100
	s_addc_u32 s77, s79, 0
	s_and_b64 s[20:21], s[62:63], exec
	s_cselect_b32 s76, s86, s76
	s_cselect_b32 s77, s41, s77
	s_add_u32 s20, s56, s68
	s_addc_u32 s21, s57, s69
	s_add_u32 s68, s20, 0x100
	s_addc_u32 s69, s21, 0
	s_add_i32 vcc_lo, 0, 0x10000
	s_and_b64 s[20:21], s[62:63], exec
	s_cselect_b32 s62, s87, s68
	s_cselect_b32 s63, s49, s69
	s_add_i32 s21, 0, 0x14000
	v_add_u32_e32 v148, vcc_lo, v133
	v_add_u32_e32 v182, s21, v133
	ds_read_b128 v[136:139], v148
	ds_read_b128 v[140:143], v148 offset:1024
	ds_read_b128 v[144:147], v148 offset:2048
	ds_read_b128 v[148:151], v148 offset:3072
	ds_read_b128 v[152:155], v182
	ds_read_b128 v[156:159], v182 offset:1024
	ds_read_b128 v[160:163], v182 offset:2048
	ds_read_b128 v[182:185], v182 offset:3072
	s_add_i32 s93, 0, 0x18000
	s_add_i32 s69, 0, 0x1c000
	s_add_i32 s20, s93, s46
	s_add_i32 s97, vcc_lo, s46
	s_add_i32 s95, s21, s46
	s_add_i32 s68, s20, 0x2000
	s_add_i32 vcc_hi, s69, s46
	s_add_i32 m0, s22, 0xc000
	s_add_i32 s47, s22, 0xe000
	s_add_i32 s96, s97, 0x2000
	s_add_i32 s94, s95, 0x2000
	s_add_i32 vcc_lo, vcc_hi, 0x2000
	v_lshl_add_u64 v[202:203], s[78:79], 0, v[130:131]
	v_lshl_add_u64 v[230:231], v[202:203], 0, s[80:81]
	ds_read_b128 v[186:189], v135
	ds_read_b128 v[190:193], v135 offset:1024
	ds_read_b128 v[194:197], v135 offset:2048
	ds_read_b128 v[198:201], v135 offset:3072
	ds_read_b128 v[214:217], v135 offset:4096
	ds_read_b128 v[218:221], v135 offset:5120
	ds_read_b128 v[222:225], v135 offset:6144
	ds_read_b128 v[226:229], v135 offset:7168
	global_load_lds_dwordx4 v[230:231], off
	v_lshl_add_u64 v[202:203], v[202:203], 0, s[30:31]
	s_mov_b32 m0, s47
	s_nop 0
	global_load_lds_dwordx4 v[202:203], off
	s_waitcnt vmcnt(8)
	s_waitcnt lgkmcnt(0)
	s_barrier
	s_setprio 1
	s_waitcnt lgkmcnt(0)
	v_mfma_f32_16x16x32_bf16 v[126:129], v[136:139], v[186:189], v[126:129]
	v_mfma_f32_16x16x32_bf16 v[126:129], v[140:143], v[190:193], v[126:129]
	v_mfma_f32_16x16x32_bf16 v[122:125], v[144:147], v[186:189], v[122:125]
	v_mfma_f32_16x16x32_bf16 v[122:125], v[148:151], v[190:193], v[122:125]
	v_mfma_f32_16x16x32_bf16 v[118:121], v[136:139], v[194:197], v[118:121]
	v_mfma_f32_16x16x32_bf16 v[118:121], v[140:143], v[198:201], v[118:121]
	v_mfma_f32_16x16x32_bf16 v[110:113], v[144:147], v[194:197], v[110:113]
	v_mfma_f32_16x16x32_bf16 v[110:113], v[148:151], v[198:201], v[110:113]
	v_mfma_f32_16x16x32_bf16 v[102:105], v[136:139], v[214:217], v[102:105]
	v_mfma_f32_16x16x32_bf16 v[102:105], v[140:143], v[218:221], v[102:105]
	v_mfma_f32_16x16x32_bf16 v[94:97], v[144:147], v[214:217], v[94:97]
	v_mfma_f32_16x16x32_bf16 v[94:97], v[148:151], v[218:221], v[94:97]
	v_mfma_f32_16x16x32_bf16 v[86:89], v[136:139], v[222:225], v[86:89]
	v_mfma_f32_16x16x32_bf16 v[86:89], v[140:143], v[226:229], v[86:89]
	v_mfma_f32_16x16x32_bf16 v[78:81], v[144:147], v[222:225], v[78:81]
	v_mfma_f32_16x16x32_bf16 v[78:81], v[148:151], v[226:229], v[78:81]
	s_setprio 0
	s_setprio 1
	v_mfma_f32_16x16x32_bf16 v[114:117], v[152:155], v[186:189], v[114:117]
	v_mfma_f32_16x16x32_bf16 v[114:117], v[156:159], v[190:193], v[114:117]
	v_mfma_f32_16x16x32_bf16 v[106:109], v[160:163], v[186:189], v[106:109]
	v_mfma_f32_16x16x32_bf16 v[106:109], v[182:185], v[190:193], v[106:109]
	v_mfma_f32_16x16x32_bf16 v[98:101], v[152:155], v[194:197], v[98:101]
	v_mfma_f32_16x16x32_bf16 v[98:101], v[156:159], v[198:201], v[98:101]
	v_mfma_f32_16x16x32_bf16 v[90:93], v[160:163], v[194:197], v[90:93]
	v_mfma_f32_16x16x32_bf16 v[90:93], v[182:185], v[198:201], v[90:93]
	v_mfma_f32_16x16x32_bf16 v[82:85], v[152:155], v[214:217], v[82:85]
	v_mfma_f32_16x16x32_bf16 v[82:85], v[156:159], v[218:221], v[82:85]
	v_mfma_f32_16x16x32_bf16 v[74:77], v[160:163], v[214:217], v[74:77]
	v_mfma_f32_16x16x32_bf16 v[74:77], v[182:185], v[218:221], v[74:77]
	v_mfma_f32_16x16x32_bf16 v[70:73], v[152:155], v[222:225], v[70:73]
	v_mfma_f32_16x16x32_bf16 v[70:73], v[156:159], v[226:229], v[70:73]
	v_mfma_f32_16x16x32_bf16 v[66:69], v[160:163], v[222:225], v[66:69]
	v_mfma_f32_16x16x32_bf16 v[66:69], v[182:185], v[226:229], v[66:69]
	s_setprio 0
	s_barrier
	s_mov_b32 m0, s97
	v_lshl_add_u64 v[202:203], s[62:63], 0, v[0:1]
	ds_read_b128 v[186:189], v135 offset:16384
	ds_read_b128 v[190:193], v135 offset:17408
	ds_read_b128 v[194:197], v135 offset:18432
	ds_read_b128 v[198:201], v135 offset:19456
	ds_read_b128 v[214:217], v135 offset:20480
	ds_read_b128 v[218:221], v135 offset:21504
	ds_read_b128 v[222:225], v135 offset:22528
	ds_read_b128 v[226:229], v135 offset:23552
	global_load_lds_dwordx4 v[202:203], off
	v_lshl_add_u64 v[230:231], v[202:203], 0, s[36:37]
	s_mov_b32 m0, s96
	s_nop 0
	global_load_lds_dwordx4 v[230:231], off
	v_lshl_add_u64 v[230:231], v[202:203], 0, s[64:65]
	s_mov_b32 m0, s95
	s_nop 0
	global_load_lds_dwordx4 v[230:231], off
	v_lshl_add_u64 v[230:231], v[202:203], 0, s[8:9]
	s_mov_b32 m0, s94
	s_nop 0
	global_load_lds_dwordx4 v[230:231], off
	v_lshl_add_u64 v[230:231], s[76:77], 0, v[130:131]
	s_mov_b32 m0, s22
	v_lshl_add_u64 v[232:233], v[230:231], 0, s[36:37]
	global_load_lds_dwordx4 v[230:231], off
	s_mov_b32 m0, s88
	s_nop 0
	global_load_lds_dwordx4 v[232:233], off
	s_waitcnt vmcnt(8)
	s_waitcnt lgkmcnt(0)
	s_barrier
	s_setprio 1
	s_waitcnt lgkmcnt(0)
	v_mfma_f32_16x16x32_bf16 v[62:65], v[136:139], v[186:189], v[62:65]
	v_mfma_f32_16x16x32_bf16 v[62:65], v[140:143], v[190:193], v[62:65]
	v_mfma_f32_16x16x32_bf16 v[58:61], v[144:147], v[186:189], v[58:61]
	v_mfma_f32_16x16x32_bf16 v[58:61], v[148:151], v[190:193], v[58:61]
	v_mfma_f32_16x16x32_bf16 v[54:57], v[136:139], v[194:197], v[54:57]
	v_mfma_f32_16x16x32_bf16 v[54:57], v[140:143], v[198:201], v[54:57]
	v_mfma_f32_16x16x32_bf16 v[46:49], v[144:147], v[194:197], v[46:49]
	v_mfma_f32_16x16x32_bf16 v[46:49], v[148:151], v[198:201], v[46:49]
	v_mfma_f32_16x16x32_bf16 v[38:41], v[136:139], v[214:217], v[38:41]
	v_mfma_f32_16x16x32_bf16 v[38:41], v[140:143], v[218:221], v[38:41]
	v_mfma_f32_16x16x32_bf16 v[30:33], v[144:147], v[214:217], v[30:33]
	v_mfma_f32_16x16x32_bf16 v[30:33], v[148:151], v[218:221], v[30:33]
	v_mfma_f32_16x16x32_bf16 v[22:25], v[136:139], v[222:225], v[22:25]
	v_mfma_f32_16x16x32_bf16 v[22:25], v[140:143], v[226:229], v[22:25]
	v_mfma_f32_16x16x32_bf16 v[14:17], v[144:147], v[222:225], v[14:17]
	v_mfma_f32_16x16x32_bf16 v[14:17], v[148:151], v[226:229], v[14:17]
	s_setprio 0
	s_setprio 1
	v_mfma_f32_16x16x32_bf16 v[50:53], v[152:155], v[186:189], v[50:53]
	v_mfma_f32_16x16x32_bf16 v[50:53], v[156:159], v[190:193], v[50:53]
	v_mfma_f32_16x16x32_bf16 v[42:45], v[160:163], v[186:189], v[42:45]
	v_mfma_f32_16x16x32_bf16 v[42:45], v[182:185], v[190:193], v[42:45]
	v_mfma_f32_16x16x32_bf16 v[34:37], v[152:155], v[194:197], v[34:37]
	v_mfma_f32_16x16x32_bf16 v[34:37], v[156:159], v[198:201], v[34:37]
	v_mfma_f32_16x16x32_bf16 v[26:29], v[160:163], v[194:197], v[26:29]
	v_mfma_f32_16x16x32_bf16 v[26:29], v[182:185], v[198:201], v[26:29]
	v_mfma_f32_16x16x32_bf16 v[18:21], v[152:155], v[214:217], v[18:21]
	v_mfma_f32_16x16x32_bf16 v[18:21], v[156:159], v[218:221], v[18:21]
	v_mfma_f32_16x16x32_bf16 v[10:13], v[160:163], v[214:217], v[10:13]
	v_mfma_f32_16x16x32_bf16 v[10:13], v[182:185], v[218:221], v[10:13]
	v_mfma_f32_16x16x32_bf16 v[6:9], v[152:155], v[222:225], v[6:9]
	v_mfma_f32_16x16x32_bf16 v[6:9], v[156:159], v[226:229], v[6:9]
	v_mfma_f32_16x16x32_bf16 v[2:5], v[160:163], v[222:225], v[2:5]
	v_mfma_f32_16x16x32_bf16 v[2:5], v[182:185], v[226:229], v[2:5]
	s_setprio 0
	s_barrier
	v_add_u32_e32 v148, s93, v133
	v_add_u32_e32 v182, s69, v133
	ds_read_b128 v[136:139], v148
	ds_read_b128 v[140:143], v148 offset:1024
	ds_read_b128 v[144:147], v148 offset:2048
	ds_read_b128 v[148:151], v148 offset:3072
	ds_read_b128 v[152:155], v182
	ds_read_b128 v[156:159], v182 offset:1024
	ds_read_b128 v[160:163], v182 offset:2048
	ds_read_b128 v[182:185], v182 offset:3072
	s_mov_b32 m0, s89
	v_lshl_add_u64 v[232:233], v[230:231], 0, s[64:65]
	ds_read_b128 v[186:189], v135 offset:32768
	ds_read_b128 v[190:193], v135 offset:33792
	ds_read_b128 v[194:197], v135 offset:34816
	ds_read_b128 v[198:201], v135 offset:35840
	ds_read_b128 v[214:217], v135 offset:36864
	ds_read_b128 v[218:221], v135 offset:37888
	ds_read_b128 v[222:225], v135 offset:38912
	ds_read_b128 v[226:229], v135 offset:39936
	global_load_lds_dwordx4 v[232:233], off
	v_lshl_add_u64 v[232:233], v[230:231], 0, s[8:9]
	s_mov_b32 m0, s90
	s_nop 0
	global_load_lds_dwordx4 v[232:233], off
	s_waitcnt vmcnt(8)
	s_waitcnt lgkmcnt(0)
	s_barrier
	s_setprio 1
	s_waitcnt lgkmcnt(0)
	v_mfma_f32_16x16x32_bf16 v[126:129], v[136:139], v[186:189], v[126:129]
	v_mfma_f32_16x16x32_bf16 v[126:129], v[140:143], v[190:193], v[126:129]
	v_mfma_f32_16x16x32_bf16 v[122:125], v[144:147], v[186:189], v[122:125]
	v_mfma_f32_16x16x32_bf16 v[122:125], v[148:151], v[190:193], v[122:125]
	v_mfma_f32_16x16x32_bf16 v[118:121], v[136:139], v[194:197], v[118:121]
	v_mfma_f32_16x16x32_bf16 v[118:121], v[140:143], v[198:201], v[118:121]
	v_mfma_f32_16x16x32_bf16 v[110:113], v[144:147], v[194:197], v[110:113]
	v_mfma_f32_16x16x32_bf16 v[110:113], v[148:151], v[198:201], v[110:113]
	v_mfma_f32_16x16x32_bf16 v[102:105], v[136:139], v[214:217], v[102:105]
	v_mfma_f32_16x16x32_bf16 v[102:105], v[140:143], v[218:221], v[102:105]
	v_mfma_f32_16x16x32_bf16 v[94:97], v[144:147], v[214:217], v[94:97]
	v_mfma_f32_16x16x32_bf16 v[94:97], v[148:151], v[218:221], v[94:97]
	v_mfma_f32_16x16x32_bf16 v[86:89], v[136:139], v[222:225], v[86:89]
	v_mfma_f32_16x16x32_bf16 v[86:89], v[140:143], v[226:229], v[86:89]
	v_mfma_f32_16x16x32_bf16 v[78:81], v[144:147], v[222:225], v[78:81]
	v_mfma_f32_16x16x32_bf16 v[78:81], v[148:151], v[226:229], v[78:81]
	s_setprio 0
	s_setprio 1
	v_mfma_f32_16x16x32_bf16 v[114:117], v[152:155], v[186:189], v[114:117]
	v_mfma_f32_16x16x32_bf16 v[114:117], v[156:159], v[190:193], v[114:117]
	v_mfma_f32_16x16x32_bf16 v[106:109], v[160:163], v[186:189], v[106:109]
	v_mfma_f32_16x16x32_bf16 v[106:109], v[182:185], v[190:193], v[106:109]
	v_mfma_f32_16x16x32_bf16 v[98:101], v[152:155], v[194:197], v[98:101]
	v_mfma_f32_16x16x32_bf16 v[98:101], v[156:159], v[198:201], v[98:101]
	v_mfma_f32_16x16x32_bf16 v[90:93], v[160:163], v[194:197], v[90:93]
	v_mfma_f32_16x16x32_bf16 v[90:93], v[182:185], v[198:201], v[90:93]
	v_mfma_f32_16x16x32_bf16 v[82:85], v[152:155], v[214:217], v[82:85]
	v_mfma_f32_16x16x32_bf16 v[82:85], v[156:159], v[218:221], v[82:85]
	v_mfma_f32_16x16x32_bf16 v[74:77], v[160:163], v[214:217], v[74:77]
	v_mfma_f32_16x16x32_bf16 v[74:77], v[182:185], v[218:221], v[74:77]
	v_mfma_f32_16x16x32_bf16 v[70:73], v[152:155], v[222:225], v[70:73]
	v_mfma_f32_16x16x32_bf16 v[70:73], v[156:159], v[226:229], v[70:73]
	v_mfma_f32_16x16x32_bf16 v[66:69], v[160:163], v[222:225], v[66:69]
	v_mfma_f32_16x16x32_bf16 v[66:69], v[182:185], v[226:229], v[66:69]
	s_setprio 0
	s_barrier
	s_mov_b32 m0, s20
	v_lshl_add_u64 v[232:233], v[202:203], 0, s[34:35]
	ds_read_b128 v[186:189], v135 offset:49152
	ds_read_b128 v[190:193], v135 offset:50176
	ds_read_b128 v[194:197], v135 offset:51200
	ds_read_b128 v[198:201], v135 offset:52224
	ds_read_b128 v[214:217], v135 offset:53248
	ds_read_b128 v[218:221], v135 offset:54272
	ds_read_b128 v[222:225], v135 offset:55296
	ds_read_b128 v[226:229], v135 offset:56320
	global_load_lds_dwordx4 v[232:233], off
	v_lshl_add_u64 v[232:233], v[202:203], 0, s[70:71]
	s_mov_b32 m0, s68
	s_nop 0
	global_load_lds_dwordx4 v[232:233], off
	v_lshl_add_u64 v[232:233], v[202:203], 0, s[80:81]
	s_mov_b32 m0, vcc_hi
	v_lshl_add_u64 v[202:203], v[202:203], 0, s[30:31]
	global_load_lds_dwordx4 v[232:233], off
	s_mov_b32 m0, vcc_lo
	s_nop 0
	global_load_lds_dwordx4 v[202:203], off
	v_lshl_add_u64 v[202:203], v[230:231], 0, s[34:35]
	s_mov_b32 m0, s91
	s_nop 0
	global_load_lds_dwordx4 v[202:203], off
	v_lshl_add_u64 v[202:203], v[230:231], 0, s[70:71]
	s_mov_b32 m0, s92
	s_nop 0
	global_load_lds_dwordx4 v[202:203], off
	s_waitcnt vmcnt(8)
	s_waitcnt lgkmcnt(0)
	s_barrier
	s_setprio 1
	s_waitcnt lgkmcnt(0)
	v_mfma_f32_16x16x32_bf16 v[62:65], v[136:139], v[186:189], v[62:65]
	v_mfma_f32_16x16x32_bf16 v[62:65], v[140:143], v[190:193], v[62:65]
	v_mfma_f32_16x16x32_bf16 v[58:61], v[144:147], v[186:189], v[58:61]
	v_mfma_f32_16x16x32_bf16 v[58:61], v[148:151], v[190:193], v[58:61]
	v_mfma_f32_16x16x32_bf16 v[54:57], v[136:139], v[194:197], v[54:57]
	v_mfma_f32_16x16x32_bf16 v[54:57], v[140:143], v[198:201], v[54:57]
	v_mfma_f32_16x16x32_bf16 v[46:49], v[144:147], v[194:197], v[46:49]
	v_mfma_f32_16x16x32_bf16 v[46:49], v[148:151], v[198:201], v[46:49]
	v_mfma_f32_16x16x32_bf16 v[38:41], v[136:139], v[214:217], v[38:41]
	v_mfma_f32_16x16x32_bf16 v[38:41], v[140:143], v[218:221], v[38:41]
	v_mfma_f32_16x16x32_bf16 v[30:33], v[144:147], v[214:217], v[30:33]
	v_mfma_f32_16x16x32_bf16 v[30:33], v[148:151], v[218:221], v[30:33]
	v_mfma_f32_16x16x32_bf16 v[22:25], v[136:139], v[222:225], v[22:25]
	v_mfma_f32_16x16x32_bf16 v[22:25], v[140:143], v[226:229], v[22:25]
	v_mfma_f32_16x16x32_bf16 v[14:17], v[144:147], v[222:225], v[14:17]
	v_mfma_f32_16x16x32_bf16 v[14:17], v[148:151], v[226:229], v[14:17]
	s_setprio 0
	s_setprio 1
	v_mfma_f32_16x16x32_bf16 v[50:53], v[152:155], v[186:189], v[50:53]
	v_mfma_f32_16x16x32_bf16 v[50:53], v[156:159], v[190:193], v[50:53]
	v_mfma_f32_16x16x32_bf16 v[42:45], v[160:163], v[186:189], v[42:45]
	v_mfma_f32_16x16x32_bf16 v[42:45], v[182:185], v[190:193], v[42:45]
	v_mfma_f32_16x16x32_bf16 v[34:37], v[152:155], v[194:197], v[34:37]
	v_mfma_f32_16x16x32_bf16 v[34:37], v[156:159], v[198:201], v[34:37]
	v_mfma_f32_16x16x32_bf16 v[26:29], v[160:163], v[194:197], v[26:29]
	v_mfma_f32_16x16x32_bf16 v[26:29], v[182:185], v[198:201], v[26:29]
	v_mfma_f32_16x16x32_bf16 v[18:21], v[152:155], v[214:217], v[18:21]
	v_mfma_f32_16x16x32_bf16 v[18:21], v[156:159], v[218:221], v[18:21]
	v_mfma_f32_16x16x32_bf16 v[10:13], v[160:163], v[214:217], v[10:13]
	v_mfma_f32_16x16x32_bf16 v[10:13], v[182:185], v[218:221], v[10:13]
	v_mfma_f32_16x16x32_bf16 v[6:9], v[152:155], v[222:225], v[6:9]
	v_mfma_f32_16x16x32_bf16 v[6:9], v[156:159], v[226:229], v[6:9]
	v_mfma_f32_16x16x32_bf16 v[2:5], v[160:163], v[222:225], v[2:5]
	v_mfma_f32_16x16x32_bf16 v[2:5], v[182:185], v[226:229], v[2:5]
	s_setprio 0
	s_barrier
	s_andn2_b64 vcc, exec, s[60:61]
	s_mov_b64 s[62:63], -1
	s_mov_b64 s[60:61], 0
	s_mov_b64 s[68:69], 0x100
	s_cbranch_vccz .LBB0_1052
	s_and_b64 vcc, exec, s[6:7]
	s_cbranch_vccz .LBB0_1055
	s_barrier
